# GEMM K-loops (6 loops): counter/pointer increments and exit compare moved in front of the loop-back barrier (back-edge rotation), on the v042 stack
# baseline (speedup 1.0000x reference)
.LBB0_290:
	ds_read_b128 v[154:157], v150
	ds_read_b128 v[158:161], v150 offset:1024
	ds_read_b128 v[162:165], v150 offset:2048
	ds_read_b128 v[166:169], v150 offset:3072
	ds_read_b128 v[170:173], v151
	ds_read_b128 v[174:177], v151 offset:1024
	ds_read_b128 v[178:181], v151 offset:2048
	ds_read_b128 v[182:185], v151 offset:3072
	s_add_u32 s44, s50, 0xfff00080
	s_addc_u32 s45, s51, -1
	s_cmp_eq_u32 s74, 60
	s_cselect_b32 s55, s37, s45
	s_cselect_b32 s54, s70, s44
	s_cselect_b32 s53, s27, s73
	s_cselect_b32 s52, s71, s72
	v_lshl_add_u64 v[146:147], s[50:51], 0, v[138:139]
	s_add_i32 m0, s43, 0xc000
	ds_read_b128 v[186:189], v152
	ds_read_b128 v[190:193], v152 offset:1024
	ds_read_b128 v[194:197], v152 offset:2048
	ds_read_b128 v[198:201], v152 offset:3072
	ds_read_b128 v[202:205], v152 offset:4096
	ds_read_b128 v[206:209], v152 offset:5120
	ds_read_b128 v[210:213], v152 offset:6144
	ds_read_b128 v[214:217], v152 offset:7168
	global_load_lds_dwordx4 v[146:147], off
	v_lshl_add_u64 v[146:147], s[50:51], 0, v[140:141]
	s_add_i32 m0, s43, 0xe000
	s_nop 0
	global_load_lds_dwordx4 v[146:147], off
	s_waitcnt vmcnt(8)
	s_waitcnt lgkmcnt(0)
	s_barrier
	s_setprio 1
	s_waitcnt lgkmcnt(0)
	v_mfma_f32_16x16x32_bf16 v[126:129], v[154:157], v[186:189], v[126:129]
	v_mfma_f32_16x16x32_bf16 v[122:125], v[162:165], v[186:189], v[122:125]
	v_mfma_f32_16x16x32_bf16 v[118:121], v[154:157], v[194:197], v[118:121]
	v_mfma_f32_16x16x32_bf16 v[110:113], v[162:165], v[194:197], v[110:113]
	v_mfma_f32_16x16x32_bf16 v[102:105], v[154:157], v[202:205], v[102:105]
	v_mfma_f32_16x16x32_bf16 v[94:97], v[162:165], v[202:205], v[94:97]
	v_mfma_f32_16x16x32_bf16 v[86:89], v[154:157], v[210:213], v[86:89]
	v_mfma_f32_16x16x32_bf16 v[78:81], v[162:165], v[210:213], v[78:81]
	v_mfma_f32_16x16x32_bf16 v[126:129], v[158:161], v[190:193], v[126:129]
	v_mfma_f32_16x16x32_bf16 v[122:125], v[166:169], v[190:193], v[122:125]
	v_mfma_f32_16x16x32_bf16 v[118:121], v[158:161], v[198:201], v[118:121]
	v_mfma_f32_16x16x32_bf16 v[110:113], v[166:169], v[198:201], v[110:113]
	v_mfma_f32_16x16x32_bf16 v[102:105], v[158:161], v[206:209], v[102:105]
	v_mfma_f32_16x16x32_bf16 v[94:97], v[166:169], v[206:209], v[94:97]
	v_mfma_f32_16x16x32_bf16 v[86:89], v[158:161], v[214:217], v[86:89]
	v_mfma_f32_16x16x32_bf16 v[78:81], v[166:169], v[214:217], v[78:81]
	s_setprio 0
	s_setprio 1
	v_mfma_f32_16x16x32_bf16 v[114:117], v[170:173], v[186:189], v[114:117]
	v_mfma_f32_16x16x32_bf16 v[106:109], v[178:181], v[186:189], v[106:109]
	v_mfma_f32_16x16x32_bf16 v[98:101], v[170:173], v[194:197], v[98:101]
	v_mfma_f32_16x16x32_bf16 v[90:93], v[178:181], v[194:197], v[90:93]
	v_mfma_f32_16x16x32_bf16 v[82:85], v[170:173], v[202:205], v[82:85]
	v_mfma_f32_16x16x32_bf16 v[74:77], v[178:181], v[202:205], v[74:77]
	v_mfma_f32_16x16x32_bf16 v[70:73], v[170:173], v[210:213], v[70:73]
	v_mfma_f32_16x16x32_bf16 v[66:69], v[178:181], v[210:213], v[66:69]
	v_mfma_f32_16x16x32_bf16 v[114:117], v[174:177], v[190:193], v[114:117]
	v_mfma_f32_16x16x32_bf16 v[106:109], v[182:185], v[190:193], v[106:109]
	v_mfma_f32_16x16x32_bf16 v[98:101], v[174:177], v[198:201], v[98:101]
	v_mfma_f32_16x16x32_bf16 v[90:93], v[182:185], v[198:201], v[90:93]
	v_mfma_f32_16x16x32_bf16 v[82:85], v[174:177], v[206:209], v[82:85]
	v_mfma_f32_16x16x32_bf16 v[74:77], v[182:185], v[206:209], v[74:77]
	v_mfma_f32_16x16x32_bf16 v[70:73], v[174:177], v[214:217], v[70:73]
	v_mfma_f32_16x16x32_bf16 v[66:69], v[182:185], v[214:217], v[66:69]
	s_setprio 0
	s_barrier
	s_add_i32 s44, s63, s49
	v_lshl_add_u64 v[146:147], s[52:53], 0, v[134:135]
	s_mov_b32 m0, s44
	ds_read_b128 v[186:189], v152 offset:16384
	ds_read_b128 v[190:193], v152 offset:17408
	ds_read_b128 v[194:197], v152 offset:18432
	ds_read_b128 v[198:201], v152 offset:19456
	ds_read_b128 v[202:205], v152 offset:20480
	ds_read_b128 v[206:209], v152 offset:21504
	ds_read_b128 v[210:213], v152 offset:22528
	ds_read_b128 v[214:217], v152 offset:23552
	global_load_lds_dwordx4 v[146:147], off
	s_add_i32 m0, s44, 0x2000
	s_add_u32 s76, s52, 0x100000
	v_lshl_add_u64 v[218:219], s[52:53], 0, v[130:131]
	s_addc_u32 s77, s53, 0
	s_add_i32 s44, s64, s49
	global_load_lds_dwordx4 v[218:219], off
	v_lshl_add_u64 v[220:221], s[76:77], 0, v[134:135]
	s_mov_b32 m0, s44
	v_lshl_add_u64 v[222:223], s[54:55], 0, v[132:133]
	global_load_lds_dwordx4 v[220:221], off
	v_lshl_add_u64 v[220:221], s[76:77], 0, v[130:131]
	s_add_i32 m0, s44, 0x2000
	s_nop 0
	global_load_lds_dwordx4 v[220:221], off
	v_lshl_add_u64 v[220:221], s[54:55], 0, v[136:137]
	s_mov_b32 m0, s43
	s_nop 0
	global_load_lds_dwordx4 v[220:221], off
	s_mov_b32 m0, s57
	s_nop 0
	global_load_lds_dwordx4 v[222:223], off
	s_waitcnt vmcnt(8)
	s_waitcnt lgkmcnt(0)
	s_barrier
	s_setprio 1
	s_waitcnt lgkmcnt(0)
	v_mfma_f32_16x16x32_bf16 v[62:65], v[154:157], v[186:189], v[62:65]
	v_mfma_f32_16x16x32_bf16 v[58:61], v[162:165], v[186:189], v[58:61]
	v_mfma_f32_16x16x32_bf16 v[54:57], v[154:157], v[194:197], v[54:57]
	v_mfma_f32_16x16x32_bf16 v[46:49], v[162:165], v[194:197], v[46:49]
	v_mfma_f32_16x16x32_bf16 v[38:41], v[154:157], v[202:205], v[38:41]
	v_mfma_f32_16x16x32_bf16 v[30:33], v[162:165], v[202:205], v[30:33]
	v_mfma_f32_16x16x32_bf16 v[22:25], v[154:157], v[210:213], v[22:25]
	v_mfma_f32_16x16x32_bf16 v[14:17], v[162:165], v[210:213], v[14:17]
	v_mfma_f32_16x16x32_bf16 v[62:65], v[158:161], v[190:193], v[62:65]
	v_mfma_f32_16x16x32_bf16 v[58:61], v[166:169], v[190:193], v[58:61]
	v_mfma_f32_16x16x32_bf16 v[54:57], v[158:161], v[198:201], v[54:57]
	v_mfma_f32_16x16x32_bf16 v[46:49], v[166:169], v[198:201], v[46:49]
	v_mfma_f32_16x16x32_bf16 v[38:41], v[158:161], v[206:209], v[38:41]
	v_mfma_f32_16x16x32_bf16 v[30:33], v[166:169], v[206:209], v[30:33]
	v_mfma_f32_16x16x32_bf16 v[22:25], v[158:161], v[214:217], v[22:25]
	v_mfma_f32_16x16x32_bf16 v[14:17], v[166:169], v[214:217], v[14:17]
	s_setprio 0
	s_setprio 1
	v_mfma_f32_16x16x32_bf16 v[50:53], v[170:173], v[186:189], v[50:53]
	v_mfma_f32_16x16x32_bf16 v[42:45], v[178:181], v[186:189], v[42:45]
	v_mfma_f32_16x16x32_bf16 v[34:37], v[170:173], v[194:197], v[34:37]
	v_mfma_f32_16x16x32_bf16 v[26:29], v[178:181], v[194:197], v[26:29]
	v_mfma_f32_16x16x32_bf16 v[18:21], v[170:173], v[202:205], v[18:21]
	v_mfma_f32_16x16x32_bf16 v[10:13], v[178:181], v[202:205], v[10:13]
	v_mfma_f32_16x16x32_bf16 v[6:9], v[170:173], v[210:213], v[6:9]
	v_mfma_f32_16x16x32_bf16 v[2:5], v[178:181], v[210:213], v[2:5]
	v_mfma_f32_16x16x32_bf16 v[50:53], v[174:177], v[190:193], v[50:53]
	v_mfma_f32_16x16x32_bf16 v[42:45], v[182:185], v[190:193], v[42:45]
	v_mfma_f32_16x16x32_bf16 v[34:37], v[174:177], v[198:201], v[34:37]
	v_mfma_f32_16x16x32_bf16 v[26:29], v[182:185], v[198:201], v[26:29]
	v_mfma_f32_16x16x32_bf16 v[18:21], v[174:177], v[206:209], v[18:21]
	v_mfma_f32_16x16x32_bf16 v[10:13], v[182:185], v[206:209], v[10:13]
	v_mfma_f32_16x16x32_bf16 v[6:9], v[174:177], v[214:217], v[6:9]
	v_mfma_f32_16x16x32_bf16 v[2:5], v[182:185], v[214:217], v[2:5]
	s_setprio 0
	s_barrier
	s_add_i32 s44, 0, 0x18000
	v_add_u32_e32 v153, s44, v148
	s_add_i32 s45, 0, 0x1c000
	ds_read_b128 v[154:157], v153
	ds_read_b128 v[158:161], v153 offset:1024
	ds_read_b128 v[162:165], v153 offset:2048
	ds_read_b128 v[166:169], v153 offset:3072
	v_add_u32_e32 v153, s45, v148
	ds_read_b128 v[170:173], v153
	ds_read_b128 v[174:177], v153 offset:1024
	ds_read_b128 v[178:181], v153 offset:2048
	ds_read_b128 v[182:185], v153 offset:3072
	s_add_u32 s54, s54, 0x100000
	s_addc_u32 s55, s55, 0
	s_mov_b32 m0, s58
	v_lshl_add_u64 v[224:225], s[54:55], 0, v[136:137]
	ds_read_b128 v[186:189], v152 offset:32768
	ds_read_b128 v[190:193], v152 offset:33792
	ds_read_b128 v[194:197], v152 offset:34816
	ds_read_b128 v[198:201], v152 offset:35840
	ds_read_b128 v[202:205], v152 offset:36864
	ds_read_b128 v[206:209], v152 offset:37888
	ds_read_b128 v[210:213], v152 offset:38912
	ds_read_b128 v[214:217], v152 offset:39936
	global_load_lds_dwordx4 v[224:225], off
	v_lshl_add_u64 v[224:225], s[54:55], 0, v[132:133]
	s_mov_b32 m0, s59
	s_nop 0
	global_load_lds_dwordx4 v[224:225], off
	s_waitcnt vmcnt(8)
	s_waitcnt lgkmcnt(0)
	s_barrier
	s_setprio 1
	s_waitcnt lgkmcnt(0)
	v_mfma_f32_16x16x32_bf16 v[126:129], v[154:157], v[186:189], v[126:129]
	v_mfma_f32_16x16x32_bf16 v[122:125], v[162:165], v[186:189], v[122:125]
	v_mfma_f32_16x16x32_bf16 v[118:121], v[154:157], v[194:197], v[118:121]
	v_mfma_f32_16x16x32_bf16 v[110:113], v[162:165], v[194:197], v[110:113]
	v_mfma_f32_16x16x32_bf16 v[102:105], v[154:157], v[202:205], v[102:105]
	v_mfma_f32_16x16x32_bf16 v[94:97], v[162:165], v[202:205], v[94:97]
	v_mfma_f32_16x16x32_bf16 v[86:89], v[154:157], v[210:213], v[86:89]
	v_mfma_f32_16x16x32_bf16 v[78:81], v[162:165], v[210:213], v[78:81]
	v_mfma_f32_16x16x32_bf16 v[126:129], v[158:161], v[190:193], v[126:129]
	v_mfma_f32_16x16x32_bf16 v[122:125], v[166:169], v[190:193], v[122:125]
	v_mfma_f32_16x16x32_bf16 v[118:121], v[158:161], v[198:201], v[118:121]
	v_mfma_f32_16x16x32_bf16 v[110:113], v[166:169], v[198:201], v[110:113]
	v_mfma_f32_16x16x32_bf16 v[102:105], v[158:161], v[206:209], v[102:105]
	v_mfma_f32_16x16x32_bf16 v[94:97], v[166:169], v[206:209], v[94:97]
	v_mfma_f32_16x16x32_bf16 v[86:89], v[158:161], v[214:217], v[86:89]
	v_mfma_f32_16x16x32_bf16 v[78:81], v[166:169], v[214:217], v[78:81]
	s_setprio 0
	s_setprio 1
	v_mfma_f32_16x16x32_bf16 v[114:117], v[170:173], v[186:189], v[114:117]
	v_mfma_f32_16x16x32_bf16 v[106:109], v[178:181], v[186:189], v[106:109]
	v_mfma_f32_16x16x32_bf16 v[98:101], v[170:173], v[194:197], v[98:101]
	v_mfma_f32_16x16x32_bf16 v[90:93], v[178:181], v[194:197], v[90:93]
	v_mfma_f32_16x16x32_bf16 v[82:85], v[170:173], v[202:205], v[82:85]
	v_mfma_f32_16x16x32_bf16 v[74:77], v[178:181], v[202:205], v[74:77]
	v_mfma_f32_16x16x32_bf16 v[70:73], v[170:173], v[210:213], v[70:73]
	v_mfma_f32_16x16x32_bf16 v[66:69], v[178:181], v[210:213], v[66:69]
	v_mfma_f32_16x16x32_bf16 v[114:117], v[174:177], v[190:193], v[114:117]
	v_mfma_f32_16x16x32_bf16 v[106:109], v[182:185], v[190:193], v[106:109]
	v_mfma_f32_16x16x32_bf16 v[98:101], v[174:177], v[198:201], v[98:101]
	v_mfma_f32_16x16x32_bf16 v[90:93], v[182:185], v[198:201], v[90:93]
	v_mfma_f32_16x16x32_bf16 v[82:85], v[174:177], v[206:209], v[82:85]
	v_mfma_f32_16x16x32_bf16 v[74:77], v[182:185], v[206:209], v[74:77]
	v_mfma_f32_16x16x32_bf16 v[70:73], v[174:177], v[214:217], v[70:73]
	v_mfma_f32_16x16x32_bf16 v[66:69], v[182:185], v[214:217], v[66:69]
	s_setprio 0
	s_barrier
	s_add_i32 s44, s44, s49
	v_lshl_add_u64 v[146:147], v[146:147], 0, s[14:15]
	s_mov_b32 m0, s44
	ds_read_b128 v[186:189], v152 offset:49152
	ds_read_b128 v[190:193], v152 offset:50176
	ds_read_b128 v[194:197], v152 offset:51200
	ds_read_b128 v[198:201], v152 offset:52224
	ds_read_b128 v[202:205], v152 offset:53248
	ds_read_b128 v[206:209], v152 offset:54272
	ds_read_b128 v[210:213], v152 offset:55296
	ds_read_b128 v[214:217], v152 offset:56320
	global_load_lds_dwordx4 v[146:147], off
	s_add_i32 m0, s44, 0x2000
	s_add_u32 s52, s52, 0x100080
	v_lshl_add_u64 v[146:147], v[218:219], 0, s[14:15]
	s_addc_u32 s53, s53, 0
	s_add_i32 s44, s45, s49
	global_load_lds_dwordx4 v[146:147], off
	v_lshl_add_u64 v[146:147], s[52:53], 0, v[134:135]
	s_mov_b32 m0, s44
	s_nop 0
	global_load_lds_dwordx4 v[146:147], off
	v_lshl_add_u64 v[146:147], s[52:53], 0, v[130:131]
	s_add_i32 m0, s44, 0x2000
	s_nop 0
	global_load_lds_dwordx4 v[146:147], off
	v_lshl_add_u64 v[146:147], v[220:221], 0, s[14:15]
	s_mov_b32 m0, s61
	s_nop 0
	global_load_lds_dwordx4 v[146:147], off
	v_lshl_add_u64 v[146:147], v[222:223], 0, s[14:15]
	s_mov_b32 m0, s62
	s_nop 0
	global_load_lds_dwordx4 v[146:147], off
	s_waitcnt vmcnt(8)
	s_waitcnt lgkmcnt(0)
	s_barrier
	s_setprio 1
	s_waitcnt lgkmcnt(0)
	v_mfma_f32_16x16x32_bf16 v[62:65], v[154:157], v[186:189], v[62:65]
	v_mfma_f32_16x16x32_bf16 v[58:61], v[162:165], v[186:189], v[58:61]
	v_mfma_f32_16x16x32_bf16 v[54:57], v[154:157], v[194:197], v[54:57]
	v_mfma_f32_16x16x32_bf16 v[46:49], v[162:165], v[194:197], v[46:49]
	v_mfma_f32_16x16x32_bf16 v[38:41], v[154:157], v[202:205], v[38:41]
	v_mfma_f32_16x16x32_bf16 v[30:33], v[162:165], v[202:205], v[30:33]
	v_mfma_f32_16x16x32_bf16 v[22:25], v[154:157], v[210:213], v[22:25]
	v_mfma_f32_16x16x32_bf16 v[14:17], v[162:165], v[210:213], v[14:17]
	v_mfma_f32_16x16x32_bf16 v[62:65], v[158:161], v[190:193], v[62:65]
	v_mfma_f32_16x16x32_bf16 v[58:61], v[166:169], v[190:193], v[58:61]
	v_mfma_f32_16x16x32_bf16 v[54:57], v[158:161], v[198:201], v[54:57]
	v_mfma_f32_16x16x32_bf16 v[46:49], v[166:169], v[198:201], v[46:49]
	v_mfma_f32_16x16x32_bf16 v[38:41], v[158:161], v[206:209], v[38:41]
	v_mfma_f32_16x16x32_bf16 v[30:33], v[166:169], v[206:209], v[30:33]
	v_mfma_f32_16x16x32_bf16 v[22:25], v[158:161], v[214:217], v[22:25]
	v_mfma_f32_16x16x32_bf16 v[14:17], v[166:169], v[214:217], v[14:17]
	s_setprio 0
	s_setprio 1
	v_mfma_f32_16x16x32_bf16 v[50:53], v[170:173], v[186:189], v[50:53]
	v_mfma_f32_16x16x32_bf16 v[42:45], v[178:181], v[186:189], v[42:45]
	v_mfma_f32_16x16x32_bf16 v[34:37], v[170:173], v[194:197], v[34:37]
	v_mfma_f32_16x16x32_bf16 v[26:29], v[178:181], v[194:197], v[26:29]
	v_mfma_f32_16x16x32_bf16 v[18:21], v[170:173], v[202:205], v[18:21]
	v_mfma_f32_16x16x32_bf16 v[10:13], v[178:181], v[202:205], v[10:13]
	v_mfma_f32_16x16x32_bf16 v[6:9], v[170:173], v[210:213], v[6:9]
	v_mfma_f32_16x16x32_bf16 v[2:5], v[178:181], v[210:213], v[2:5]
	v_mfma_f32_16x16x32_bf16 v[50:53], v[174:177], v[190:193], v[50:53]
	v_mfma_f32_16x16x32_bf16 v[42:45], v[182:185], v[190:193], v[42:45]
	v_mfma_f32_16x16x32_bf16 v[34:37], v[174:177], v[198:201], v[34:37]
	v_mfma_f32_16x16x32_bf16 v[26:29], v[182:185], v[198:201], v[26:29]
	v_mfma_f32_16x16x32_bf16 v[18:21], v[174:177], v[206:209], v[18:21]
	v_mfma_f32_16x16x32_bf16 v[10:13], v[182:185], v[206:209], v[10:13]
	v_mfma_f32_16x16x32_bf16 v[6:9], v[174:177], v[214:217], v[6:9]
	v_mfma_f32_16x16x32_bf16 v[2:5], v[182:185], v[214:217], v[2:5]
	s_add_i32 s74, s74, 2
	s_add_u32 s50, s50, 0x100
	s_addc_u32 s51, s51, 0
	s_add_u32 s72, s72, 0x100
	s_addc_u32 s73, s73, 0
	s_cmp_lt_u32 s74, 62
	s_setprio 0
	s_barrier
	s_cbranch_scc1 .LBB0_290
	s_andn2_b64 vcc, exec, s[16:17]
	s_cbranch_vccnz .LBB0_293
	s_barrier

.LBB0_317:
	ds_read_b128 v[18:21], v190
	ds_read_b128 v[22:25], v190 offset:1024
	ds_read_b128 v[26:29], v190 offset:2048
	ds_read_b128 v[30:33], v190 offset:3072
	ds_read_b128 v[2:5], v191
	ds_read_b128 v[6:9], v191 offset:1024
	ds_read_b128 v[10:13], v191 offset:2048
	ds_read_b128 v[14:17], v191 offset:3072
	s_add_u32 s44, s54, 0xfff80080
	s_addc_u32 s45, s55, -1
	s_cmp_eq_u32 s74, 28
	s_cselect_b32 s59, s37, s45
	s_cselect_b32 s58, s53, s44
	s_cselect_b32 s57, s39, s73
	s_cselect_b32 s56, s71, s72
	v_lshl_add_u64 v[220:221], s[54:55], 0, v[172:173]
	s_add_i32 m0, s49, 0xc000
	ds_read_b128 v[180:183], v192
	ds_read_b128 v[184:187], v192 offset:1024
	ds_read_b128 v[196:199], v192 offset:2048
	ds_read_b128 v[200:203], v192 offset:3072
	ds_read_b128 v[204:207], v192 offset:4096
	ds_read_b128 v[208:211], v192 offset:5120
	ds_read_b128 v[212:215], v192 offset:6144
	ds_read_b128 v[216:219], v192 offset:7168
	global_load_lds_dwordx4 v[220:221], off
	v_lshl_add_u64 v[220:221], s[54:55], 0, v[174:175]
	s_add_i32 m0, s49, 0xe000
	s_nop 0
	global_load_lds_dwordx4 v[220:221], off
	s_waitcnt vmcnt(8)
	s_waitcnt lgkmcnt(0)
	s_barrier
	s_setprio 1
	s_waitcnt lgkmcnt(0)
	s_nop 1
	v_mfma_scale_f32_16x16x128_f8f6f4 v[158:161], v[18:25], v[180:187], v[158:161], v193, v193 op_sel_hi:[0,0,0]
	s_nop 1
	v_mfma_scale_f32_16x16x128_f8f6f4 v[154:157], v[26:33], v[180:187], v[154:157], v193, v193 op_sel_hi:[0,0,0]
	s_nop 1
	v_mfma_scale_f32_16x16x128_f8f6f4 v[142:145], v[18:25], v[196:203], v[142:145], v193, v193 op_sel_hi:[0,0,0]
	s_nop 1
	v_mfma_scale_f32_16x16x128_f8f6f4 v[138:141], v[26:33], v[196:203], v[138:141], v193, v193 op_sel_hi:[0,0,0]
	s_nop 1
	v_mfma_scale_f32_16x16x128_f8f6f4 v[126:129], v[18:25], v[204:211], v[126:129], v193, v193 op_sel_hi:[0,0,0]
	s_nop 1
	v_mfma_scale_f32_16x16x128_f8f6f4 v[122:125], v[26:33], v[204:211], v[122:125], v193, v193 op_sel_hi:[0,0,0]
	s_nop 1
	v_mfma_scale_f32_16x16x128_f8f6f4 v[110:113], v[18:25], v[212:219], v[110:113], v193, v193 op_sel_hi:[0,0,0]
	s_nop 1
	v_mfma_scale_f32_16x16x128_f8f6f4 v[106:109], v[26:33], v[212:219], v[106:109], v193, v193 op_sel_hi:[0,0,0]
	s_setprio 0
	s_setprio 1
	s_nop 1
	v_mfma_scale_f32_16x16x128_f8f6f4 v[150:153], v[2:9], v[180:187], v[150:153], v193, v193 op_sel_hi:[0,0,0]
	s_nop 1
	v_mfma_scale_f32_16x16x128_f8f6f4 v[146:149], v[10:17], v[180:187], v[146:149], v193, v193 op_sel_hi:[0,0,0]
	s_nop 1
	v_mfma_scale_f32_16x16x128_f8f6f4 v[134:137], v[2:9], v[196:203], v[134:137], v193, v193 op_sel_hi:[0,0,0]
	s_nop 1
	v_mfma_scale_f32_16x16x128_f8f6f4 v[130:133], v[10:17], v[196:203], v[130:133], v193, v193 op_sel_hi:[0,0,0]
	s_nop 1
	v_mfma_scale_f32_16x16x128_f8f6f4 v[118:121], v[2:9], v[204:211], v[118:121], v193, v193 op_sel_hi:[0,0,0]
	s_nop 1
	v_mfma_scale_f32_16x16x128_f8f6f4 v[114:117], v[10:17], v[204:211], v[114:117], v193, v193 op_sel_hi:[0,0,0]
	s_nop 1
	v_mfma_scale_f32_16x16x128_f8f6f4 v[102:105], v[2:9], v[212:219], v[102:105], v193, v193 op_sel_hi:[0,0,0]
	s_nop 1
	v_mfma_scale_f32_16x16x128_f8f6f4 v[98:101], v[10:17], v[212:219], v[98:101], v193, v193 op_sel_hi:[0,0,0]
	s_setprio 0
	s_barrier
	s_add_i32 s44, s66, s47
	v_lshl_add_u64 v[180:181], s[56:57], 0, v[164:165]
	s_mov_b32 m0, s44
	ds_read_b128 v[196:199], v192 offset:16384
	ds_read_b128 v[200:203], v192 offset:17408
	ds_read_b128 v[204:207], v192 offset:18432
	ds_read_b128 v[208:211], v192 offset:19456
	ds_read_b128 v[212:215], v192 offset:20480
	ds_read_b128 v[216:219], v192 offset:21504
	ds_read_b128 v[220:223], v192 offset:22528
	ds_read_b128 v[224:227], v192 offset:23552
	global_load_lds_dwordx4 v[180:181], off
	s_add_i32 m0, s44, 0x2000
	s_add_u32 s76, s56, 0x80000
	v_lshl_add_u64 v[182:183], s[56:57], 0, v[168:169]
	s_addc_u32 s77, s57, 0
	s_add_i32 s44, s67, s47
	global_load_lds_dwordx4 v[182:183], off
	v_lshl_add_u64 v[184:185], s[76:77], 0, v[164:165]
	s_mov_b32 m0, s44
	v_lshl_add_u64 v[186:187], s[58:59], 0, v[166:167]
	global_load_lds_dwordx4 v[184:185], off
	v_lshl_add_u64 v[184:185], s[76:77], 0, v[168:169]
	s_add_i32 m0, s44, 0x2000
	s_nop 0
	global_load_lds_dwordx4 v[184:185], off
	v_lshl_add_u64 v[184:185], s[58:59], 0, v[162:163]
	s_mov_b32 m0, s49
	s_nop 0
	global_load_lds_dwordx4 v[184:185], off
	s_mov_b32 m0, s51
	s_nop 0
	global_load_lds_dwordx4 v[186:187], off
	s_waitcnt vmcnt(8)
	s_waitcnt lgkmcnt(0)
	s_barrier
	s_setprio 1
	s_waitcnt lgkmcnt(0)
	s_nop 1
	v_mfma_scale_f32_16x16x128_f8f6f4 v[94:97], v[18:25], v[196:203], v[94:97], v193, v193 op_sel_hi:[0,0,0]
	s_nop 1
	v_mfma_scale_f32_16x16x128_f8f6f4 v[90:93], v[26:33], v[196:203], v[90:93], v193, v193 op_sel_hi:[0,0,0]
	s_nop 1
	v_mfma_scale_f32_16x16x128_f8f6f4 v[78:81], v[18:25], v[204:211], v[78:81], v193, v193 op_sel_hi:[0,0,0]
	s_nop 1
	v_mfma_scale_f32_16x16x128_f8f6f4 v[74:77], v[26:33], v[204:211], v[74:77], v193, v193 op_sel_hi:[0,0,0]
	s_nop 1
	v_mfma_scale_f32_16x16x128_f8f6f4 v[62:65], v[18:25], v[212:219], v[62:65], v193, v193 op_sel_hi:[0,0,0]
	s_nop 1
	v_mfma_scale_f32_16x16x128_f8f6f4 v[58:61], v[26:33], v[212:219], v[58:61], v193, v193 op_sel_hi:[0,0,0]
	s_nop 1
	v_mfma_scale_f32_16x16x128_f8f6f4 v[46:49], v[18:25], v[220:227], v[46:49], v193, v193 op_sel_hi:[0,0,0]
	s_nop 1
	v_mfma_scale_f32_16x16x128_f8f6f4 v[42:45], v[26:33], v[220:227], v[42:45], v193, v193 op_sel_hi:[0,0,0]
	s_setprio 0
	s_setprio 1
	s_nop 1
	v_mfma_scale_f32_16x16x128_f8f6f4 v[86:89], v[2:9], v[196:203], v[86:89], v193, v193 op_sel_hi:[0,0,0]
	s_nop 1
	v_mfma_scale_f32_16x16x128_f8f6f4 v[82:85], v[10:17], v[196:203], v[82:85], v193, v193 op_sel_hi:[0,0,0]
	s_nop 1
	v_mfma_scale_f32_16x16x128_f8f6f4 v[70:73], v[2:9], v[204:211], v[70:73], v193, v193 op_sel_hi:[0,0,0]
	s_nop 1
	v_mfma_scale_f32_16x16x128_f8f6f4 v[66:69], v[10:17], v[204:211], v[66:69], v193, v193 op_sel_hi:[0,0,0]
	s_nop 1
	v_mfma_scale_f32_16x16x128_f8f6f4 v[54:57], v[2:9], v[212:219], v[54:57], v193, v193 op_sel_hi:[0,0,0]
	s_nop 1
	v_mfma_scale_f32_16x16x128_f8f6f4 v[50:53], v[10:17], v[212:219], v[50:53], v193, v193 op_sel_hi:[0,0,0]
	s_nop 1
	v_mfma_scale_f32_16x16x128_f8f6f4 v[38:41], v[2:9], v[220:227], v[38:41], v193, v193 op_sel_hi:[0,0,0]
	s_nop 1
	v_mfma_scale_f32_16x16x128_f8f6f4 v[34:37], v[10:17], v[220:227], v[34:37], v193, v193 op_sel_hi:[0,0,0]
	s_setprio 0
	s_barrier
	s_add_i32 s44, 0, 0x18000
	s_add_i32 s45, 0, 0x1c000
	v_add_u32_e32 v14, s44, v188
	v_add_u32_e32 v30, s45, v188
	ds_read_b128 v[2:5], v14
	ds_read_b128 v[6:9], v14 offset:1024
	ds_read_b128 v[10:13], v14 offset:2048
	ds_read_b128 v[14:17], v14 offset:3072
	ds_read_b128 v[18:21], v30
	ds_read_b128 v[22:25], v30 offset:1024
	ds_read_b128 v[26:29], v30 offset:2048
	ds_read_b128 v[30:33], v30 offset:3072
	s_add_u32 s58, s58, 0x80000
	s_addc_u32 s59, s59, 0
	s_mov_b32 m0, s60
	v_lshl_add_u64 v[228:229], s[58:59], 0, v[162:163]
	ds_read_b128 v[196:199], v192 offset:32768
	ds_read_b128 v[200:203], v192 offset:33792
	ds_read_b128 v[204:207], v192 offset:34816
	ds_read_b128 v[208:211], v192 offset:35840
	ds_read_b128 v[212:215], v192 offset:36864
	ds_read_b128 v[216:219], v192 offset:37888
	ds_read_b128 v[220:223], v192 offset:38912
	ds_read_b128 v[224:227], v192 offset:39936
	global_load_lds_dwordx4 v[228:229], off
	v_lshl_add_u64 v[228:229], s[58:59], 0, v[166:167]
	s_mov_b32 m0, s61
	s_nop 0
	global_load_lds_dwordx4 v[228:229], off
	s_waitcnt vmcnt(8)
	s_waitcnt lgkmcnt(0)
	s_barrier
	s_setprio 1
	s_waitcnt lgkmcnt(0)
	s_nop 1
	v_mfma_scale_f32_16x16x128_f8f6f4 v[158:161], v[2:9], v[196:203], v[158:161], v193, v193 op_sel_hi:[0,0,0]
	s_nop 1
	v_mfma_scale_f32_16x16x128_f8f6f4 v[154:157], v[10:17], v[196:203], v[154:157], v193, v193 op_sel_hi:[0,0,0]
	s_nop 1
	v_mfma_scale_f32_16x16x128_f8f6f4 v[142:145], v[2:9], v[204:211], v[142:145], v193, v193 op_sel_hi:[0,0,0]
	s_nop 1
	v_mfma_scale_f32_16x16x128_f8f6f4 v[138:141], v[10:17], v[204:211], v[138:141], v193, v193 op_sel_hi:[0,0,0]
	s_nop 1
	v_mfma_scale_f32_16x16x128_f8f6f4 v[126:129], v[2:9], v[212:219], v[126:129], v193, v193 op_sel_hi:[0,0,0]
	s_nop 1
	v_mfma_scale_f32_16x16x128_f8f6f4 v[122:125], v[10:17], v[212:219], v[122:125], v193, v193 op_sel_hi:[0,0,0]
	s_nop 1
	v_mfma_scale_f32_16x16x128_f8f6f4 v[110:113], v[2:9], v[220:227], v[110:113], v193, v193 op_sel_hi:[0,0,0]
	s_nop 1
	v_mfma_scale_f32_16x16x128_f8f6f4 v[106:109], v[10:17], v[220:227], v[106:109], v193, v193 op_sel_hi:[0,0,0]
	s_setprio 0
	s_setprio 1
	s_nop 1
	v_mfma_scale_f32_16x16x128_f8f6f4 v[150:153], v[18:25], v[196:203], v[150:153], v193, v193 op_sel_hi:[0,0,0]
	s_nop 1
	v_mfma_scale_f32_16x16x128_f8f6f4 v[146:149], v[26:33], v[196:203], v[146:149], v193, v193 op_sel_hi:[0,0,0]
	s_nop 1
	v_mfma_scale_f32_16x16x128_f8f6f4 v[134:137], v[18:25], v[204:211], v[134:137], v193, v193 op_sel_hi:[0,0,0]
	s_nop 1
	v_mfma_scale_f32_16x16x128_f8f6f4 v[130:133], v[26:33], v[204:211], v[130:133], v193, v193 op_sel_hi:[0,0,0]
	s_nop 1
	v_mfma_scale_f32_16x16x128_f8f6f4 v[118:121], v[18:25], v[212:219], v[118:121], v193, v193 op_sel_hi:[0,0,0]
	s_nop 1
	v_mfma_scale_f32_16x16x128_f8f6f4 v[114:117], v[26:33], v[212:219], v[114:117], v193, v193 op_sel_hi:[0,0,0]
	s_nop 1
	v_mfma_scale_f32_16x16x128_f8f6f4 v[102:105], v[18:25], v[220:227], v[102:105], v193, v193 op_sel_hi:[0,0,0]
	s_nop 1
	v_mfma_scale_f32_16x16x128_f8f6f4 v[98:101], v[26:33], v[220:227], v[98:101], v193, v193 op_sel_hi:[0,0,0]
	s_setprio 0
	s_barrier
	s_add_i32 s44, s44, s47
	v_lshl_add_u64 v[180:181], v[180:181], 0, s[12:13]
	s_mov_b32 m0, s44
	ds_read_b128 v[196:199], v192 offset:49152
	ds_read_b128 v[200:203], v192 offset:50176
	ds_read_b128 v[204:207], v192 offset:51200
	ds_read_b128 v[208:211], v192 offset:52224
	ds_read_b128 v[212:215], v192 offset:53248
	ds_read_b128 v[216:219], v192 offset:54272
	ds_read_b128 v[220:223], v192 offset:55296
	ds_read_b128 v[224:227], v192 offset:56320
	global_load_lds_dwordx4 v[180:181], off
	s_add_i32 m0, s44, 0x2000
	s_add_u32 s56, s56, 0x80080
	v_lshl_add_u64 v[180:181], v[182:183], 0, s[12:13]
	s_addc_u32 s57, s57, 0
	s_add_i32 s44, s45, s47
	global_load_lds_dwordx4 v[180:181], off
	v_lshl_add_u64 v[180:181], s[56:57], 0, v[164:165]
	s_mov_b32 m0, s44
	s_nop 0
	global_load_lds_dwordx4 v[180:181], off
	v_lshl_add_u64 v[180:181], s[56:57], 0, v[168:169]
	s_add_i32 m0, s44, 0x2000
	s_nop 0
	global_load_lds_dwordx4 v[180:181], off
	v_lshl_add_u64 v[180:181], v[184:185], 0, s[12:13]
	s_mov_b32 m0, s63
	s_nop 0
	global_load_lds_dwordx4 v[180:181], off
	v_lshl_add_u64 v[180:181], v[186:187], 0, s[12:13]
	s_mov_b32 m0, s64
	s_nop 0
	global_load_lds_dwordx4 v[180:181], off
	s_waitcnt vmcnt(8)
	s_waitcnt lgkmcnt(0)
	s_barrier
	s_setprio 1
	s_waitcnt lgkmcnt(0)
	s_nop 1
	v_mfma_scale_f32_16x16x128_f8f6f4 v[94:97], v[2:9], v[196:203], v[94:97], v193, v193 op_sel_hi:[0,0,0]
	s_nop 1
	v_mfma_scale_f32_16x16x128_f8f6f4 v[90:93], v[10:17], v[196:203], v[90:93], v193, v193 op_sel_hi:[0,0,0]
	s_nop 1
	v_mfma_scale_f32_16x16x128_f8f6f4 v[78:81], v[2:9], v[204:211], v[78:81], v193, v193 op_sel_hi:[0,0,0]
	s_nop 1
	v_mfma_scale_f32_16x16x128_f8f6f4 v[74:77], v[10:17], v[204:211], v[74:77], v193, v193 op_sel_hi:[0,0,0]
	s_nop 1
	v_mfma_scale_f32_16x16x128_f8f6f4 v[62:65], v[2:9], v[212:219], v[62:65], v193, v193 op_sel_hi:[0,0,0]
	s_nop 1
	v_mfma_scale_f32_16x16x128_f8f6f4 v[58:61], v[10:17], v[212:219], v[58:61], v193, v193 op_sel_hi:[0,0,0]
	s_nop 1
	v_mfma_scale_f32_16x16x128_f8f6f4 v[46:49], v[2:9], v[220:227], v[46:49], v193, v193 op_sel_hi:[0,0,0]
	s_nop 1
	v_mfma_scale_f32_16x16x128_f8f6f4 v[42:45], v[10:17], v[220:227], v[42:45], v193, v193 op_sel_hi:[0,0,0]
	s_setprio 0
	s_setprio 1
	s_nop 1
	v_mfma_scale_f32_16x16x128_f8f6f4 v[86:89], v[18:25], v[196:203], v[86:89], v193, v193 op_sel_hi:[0,0,0]
	s_nop 1
	v_mfma_scale_f32_16x16x128_f8f6f4 v[82:85], v[26:33], v[196:203], v[82:85], v193, v193 op_sel_hi:[0,0,0]
	s_nop 1
	v_mfma_scale_f32_16x16x128_f8f6f4 v[70:73], v[18:25], v[204:211], v[70:73], v193, v193 op_sel_hi:[0,0,0]
	s_nop 1
	v_mfma_scale_f32_16x16x128_f8f6f4 v[66:69], v[26:33], v[204:211], v[66:69], v193, v193 op_sel_hi:[0,0,0]
	s_nop 1
	v_mfma_scale_f32_16x16x128_f8f6f4 v[54:57], v[18:25], v[212:219], v[54:57], v193, v193 op_sel_hi:[0,0,0]
	s_nop 1
	v_mfma_scale_f32_16x16x128_f8f6f4 v[50:53], v[26:33], v[212:219], v[50:53], v193, v193 op_sel_hi:[0,0,0]
	s_nop 1
	v_mfma_scale_f32_16x16x128_f8f6f4 v[38:41], v[18:25], v[220:227], v[38:41], v193, v193 op_sel_hi:[0,0,0]
	s_nop 1
	v_mfma_scale_f32_16x16x128_f8f6f4 v[34:37], v[26:33], v[220:227], v[34:37], v193, v193 op_sel_hi:[0,0,0]
	s_add_i32 s74, s74, 2
	s_add_u32 s54, s54, 0x100
	s_addc_u32 s55, s55, 0
	s_add_u32 s72, s72, 0x100
	s_addc_u32 s73, s73, 0
	s_cmp_lt_u32 s74, 30
	s_setprio 0
	s_barrier
	s_cbranch_scc1 .LBB0_317
	s_nop 15
	s_nop 15
	s_andn2_b64 vcc, exec, s[14:15]
	s_cbranch_vccnz .LBB0_322
	s_barrier
	v_lshl_add_u32 v2, s52, 8, v1
	s_cmp_gt_i32 s50, 5
	s_mov_b64 s[52:53], -1
	s_cbranch_scc1 .LBB0_323

.LBB0_394:
	ds_read_b128 v[18:21], v189
	ds_read_b128 v[22:25], v189 offset:1024
	ds_read_b128 v[26:29], v189 offset:2048
	ds_read_b128 v[30:33], v189 offset:3072
	ds_read_b128 v[2:5], v190
	ds_read_b128 v[6:9], v190 offset:1024
	ds_read_b128 v[10:13], v190 offset:2048
	ds_read_b128 v[14:17], v190 offset:3072
	s_add_u32 s42, s40, 0xfffe0080
	s_addc_u32 s43, s41, -1
	s_cmp_eq_u32 s68, 4
	s_cselect_b32 s51, s25, s43
	s_cselect_b32 s50, s64, s42
	s_cselect_b32 s43, s23, s67
	s_cselect_b32 s42, s65, s66
	v_lshl_add_u64 v[218:219], s[40:41], 0, v[170:171]
	s_add_i32 m0, s39, 0xc000
	ds_read_b128 v[178:181], v191
	ds_read_b128 v[182:185], v191 offset:1024
	ds_read_b128 v[194:197], v191 offset:2048
	ds_read_b128 v[198:201], v191 offset:3072
	ds_read_b128 v[202:205], v191 offset:4096
	ds_read_b128 v[206:209], v191 offset:5120
	ds_read_b128 v[210:213], v191 offset:6144
	ds_read_b128 v[214:217], v191 offset:7168
	global_load_lds_dwordx4 v[218:219], off
	v_lshl_add_u64 v[218:219], s[40:41], 0, v[172:173]
	s_add_i32 m0, s39, 0xe000
	s_nop 0
	global_load_lds_dwordx4 v[218:219], off
	s_waitcnt vmcnt(8)
	s_waitcnt lgkmcnt(0)
	s_barrier
	s_setprio 1
	s_waitcnt lgkmcnt(0)
	s_nop 1
	v_mfma_scale_f32_16x16x128_f8f6f4 v[158:161], v[18:25], v[178:185], v[158:161], v192, v192 op_sel_hi:[0,0,0]
	s_nop 1
	v_mfma_scale_f32_16x16x128_f8f6f4 v[154:157], v[26:33], v[178:185], v[154:157], v192, v192 op_sel_hi:[0,0,0]
	s_nop 1
	v_mfma_scale_f32_16x16x128_f8f6f4 v[142:145], v[18:25], v[194:201], v[142:145], v192, v192 op_sel_hi:[0,0,0]
	s_nop 1
	v_mfma_scale_f32_16x16x128_f8f6f4 v[138:141], v[26:33], v[194:201], v[138:141], v192, v192 op_sel_hi:[0,0,0]
	s_nop 1
	v_mfma_scale_f32_16x16x128_f8f6f4 v[126:129], v[18:25], v[202:209], v[126:129], v192, v192 op_sel_hi:[0,0,0]
	s_nop 1
	v_mfma_scale_f32_16x16x128_f8f6f4 v[122:125], v[26:33], v[202:209], v[122:125], v192, v192 op_sel_hi:[0,0,0]
	s_nop 1
	v_mfma_scale_f32_16x16x128_f8f6f4 v[110:113], v[18:25], v[210:217], v[110:113], v192, v192 op_sel_hi:[0,0,0]
	s_nop 1
	v_mfma_scale_f32_16x16x128_f8f6f4 v[106:109], v[26:33], v[210:217], v[106:109], v192, v192 op_sel_hi:[0,0,0]
	s_setprio 0
	s_setprio 1
	s_nop 1
	v_mfma_scale_f32_16x16x128_f8f6f4 v[150:153], v[2:9], v[178:185], v[150:153], v192, v192 op_sel_hi:[0,0,0]
	s_nop 1
	v_mfma_scale_f32_16x16x128_f8f6f4 v[146:149], v[10:17], v[178:185], v[146:149], v192, v192 op_sel_hi:[0,0,0]
	s_nop 1
	v_mfma_scale_f32_16x16x128_f8f6f4 v[134:137], v[2:9], v[194:201], v[134:137], v192, v192 op_sel_hi:[0,0,0]
	s_nop 1
	v_mfma_scale_f32_16x16x128_f8f6f4 v[130:133], v[10:17], v[194:201], v[130:133], v192, v192 op_sel_hi:[0,0,0]
	s_nop 1
	v_mfma_scale_f32_16x16x128_f8f6f4 v[118:121], v[2:9], v[202:209], v[118:121], v192, v192 op_sel_hi:[0,0,0]
	s_nop 1
	v_mfma_scale_f32_16x16x128_f8f6f4 v[114:117], v[10:17], v[202:209], v[114:117], v192, v192 op_sel_hi:[0,0,0]
	s_nop 1
	v_mfma_scale_f32_16x16x128_f8f6f4 v[102:105], v[2:9], v[210:217], v[102:105], v192, v192 op_sel_hi:[0,0,0]
	s_nop 1
	v_mfma_scale_f32_16x16x128_f8f6f4 v[98:101], v[10:17], v[210:217], v[98:101], v192, v192 op_sel_hi:[0,0,0]
	s_setprio 0
	s_barrier
	s_add_i32 s44, s59, s49
	v_lshl_add_u64 v[178:179], s[42:43], 0, v[166:167]
	s_mov_b32 m0, s44
	ds_read_b128 v[194:197], v191 offset:16384
	ds_read_b128 v[198:201], v191 offset:17408
	ds_read_b128 v[202:205], v191 offset:18432
	ds_read_b128 v[206:209], v191 offset:19456
	ds_read_b128 v[210:213], v191 offset:20480
	ds_read_b128 v[214:217], v191 offset:21504
	ds_read_b128 v[218:221], v191 offset:22528
	ds_read_b128 v[222:225], v191 offset:23552
	global_load_lds_dwordx4 v[178:179], off
	s_add_i32 m0, s44, 0x2000
	s_add_u32 s70, s42, 0x20000
	v_lshl_add_u64 v[180:181], s[42:43], 0, v[162:163]
	s_addc_u32 s71, s43, 0
	s_add_i32 s44, s60, s49
	global_load_lds_dwordx4 v[180:181], off
	v_lshl_add_u64 v[182:183], s[70:71], 0, v[166:167]
	s_mov_b32 m0, s44
	v_lshl_add_u64 v[184:185], s[50:51], 0, v[164:165]
	global_load_lds_dwordx4 v[182:183], off
	v_lshl_add_u64 v[182:183], s[70:71], 0, v[162:163]
	s_add_i32 m0, s44, 0x2000
	s_nop 0
	global_load_lds_dwordx4 v[182:183], off
	v_lshl_add_u64 v[182:183], s[50:51], 0, v[168:169]
	s_mov_b32 m0, s39
	s_nop 0
	global_load_lds_dwordx4 v[182:183], off
	s_mov_b32 m0, s53
	s_nop 0
	global_load_lds_dwordx4 v[184:185], off
	s_waitcnt vmcnt(8)
	s_waitcnt lgkmcnt(0)
	s_barrier
	s_setprio 1
	s_waitcnt lgkmcnt(0)
	s_nop 1
	v_mfma_scale_f32_16x16x128_f8f6f4 v[94:97], v[18:25], v[194:201], v[94:97], v192, v192 op_sel_hi:[0,0,0]
	s_nop 1
	v_mfma_scale_f32_16x16x128_f8f6f4 v[90:93], v[26:33], v[194:201], v[90:93], v192, v192 op_sel_hi:[0,0,0]
	s_nop 1
	v_mfma_scale_f32_16x16x128_f8f6f4 v[78:81], v[18:25], v[202:209], v[78:81], v192, v192 op_sel_hi:[0,0,0]
	s_nop 1
	v_mfma_scale_f32_16x16x128_f8f6f4 v[74:77], v[26:33], v[202:209], v[74:77], v192, v192 op_sel_hi:[0,0,0]
	s_nop 1
	v_mfma_scale_f32_16x16x128_f8f6f4 v[62:65], v[18:25], v[210:217], v[62:65], v192, v192 op_sel_hi:[0,0,0]
	s_nop 1
	v_mfma_scale_f32_16x16x128_f8f6f4 v[58:61], v[26:33], v[210:217], v[58:61], v192, v192 op_sel_hi:[0,0,0]
	s_nop 1
	v_mfma_scale_f32_16x16x128_f8f6f4 v[46:49], v[18:25], v[218:225], v[46:49], v192, v192 op_sel_hi:[0,0,0]
	s_nop 1
	v_mfma_scale_f32_16x16x128_f8f6f4 v[42:45], v[26:33], v[218:225], v[42:45], v192, v192 op_sel_hi:[0,0,0]
	s_setprio 0
	s_setprio 1
	s_nop 1
	v_mfma_scale_f32_16x16x128_f8f6f4 v[86:89], v[2:9], v[194:201], v[86:89], v192, v192 op_sel_hi:[0,0,0]
	s_nop 1
	v_mfma_scale_f32_16x16x128_f8f6f4 v[82:85], v[10:17], v[194:201], v[82:85], v192, v192 op_sel_hi:[0,0,0]
	s_nop 1
	v_mfma_scale_f32_16x16x128_f8f6f4 v[70:73], v[2:9], v[202:209], v[70:73], v192, v192 op_sel_hi:[0,0,0]
	s_nop 1
	v_mfma_scale_f32_16x16x128_f8f6f4 v[66:69], v[10:17], v[202:209], v[66:69], v192, v192 op_sel_hi:[0,0,0]
	s_nop 1
	v_mfma_scale_f32_16x16x128_f8f6f4 v[54:57], v[2:9], v[210:217], v[54:57], v192, v192 op_sel_hi:[0,0,0]
	s_nop 1
	v_mfma_scale_f32_16x16x128_f8f6f4 v[50:53], v[10:17], v[210:217], v[50:53], v192, v192 op_sel_hi:[0,0,0]
	s_nop 1
	v_mfma_scale_f32_16x16x128_f8f6f4 v[38:41], v[2:9], v[218:225], v[38:41], v192, v192 op_sel_hi:[0,0,0]
	s_nop 1
	v_mfma_scale_f32_16x16x128_f8f6f4 v[34:37], v[10:17], v[218:225], v[34:37], v192, v192 op_sel_hi:[0,0,0]
	s_setprio 0
	s_barrier
	s_add_i32 s44, 0, 0x18000
	s_add_i32 s45, 0, 0x1c000
	v_add_u32_e32 v14, s44, v187
	v_add_u32_e32 v30, s45, v187
	ds_read_b128 v[2:5], v14
	ds_read_b128 v[6:9], v14 offset:1024
	ds_read_b128 v[10:13], v14 offset:2048
	ds_read_b128 v[14:17], v14 offset:3072
	ds_read_b128 v[18:21], v30
	ds_read_b128 v[22:25], v30 offset:1024
	ds_read_b128 v[26:29], v30 offset:2048
	ds_read_b128 v[30:33], v30 offset:3072
	s_add_u32 s50, s50, 0x20000
	s_addc_u32 s51, s51, 0
	s_mov_b32 m0, s54
	v_lshl_add_u64 v[226:227], s[50:51], 0, v[168:169]
	ds_read_b128 v[194:197], v191 offset:32768
	ds_read_b128 v[198:201], v191 offset:33792
	ds_read_b128 v[202:205], v191 offset:34816
	ds_read_b128 v[206:209], v191 offset:35840
	ds_read_b128 v[210:213], v191 offset:36864
	ds_read_b128 v[214:217], v191 offset:37888
	ds_read_b128 v[218:221], v191 offset:38912
	ds_read_b128 v[222:225], v191 offset:39936
	global_load_lds_dwordx4 v[226:227], off
	v_lshl_add_u64 v[226:227], s[50:51], 0, v[164:165]
	s_mov_b32 m0, s55
	s_nop 0
	global_load_lds_dwordx4 v[226:227], off
	s_waitcnt vmcnt(8)
	s_waitcnt lgkmcnt(0)
	s_barrier
	s_setprio 1
	s_waitcnt lgkmcnt(0)
	s_nop 1
	v_mfma_scale_f32_16x16x128_f8f6f4 v[158:161], v[2:9], v[194:201], v[158:161], v192, v192 op_sel_hi:[0,0,0]
	s_nop 1
	v_mfma_scale_f32_16x16x128_f8f6f4 v[154:157], v[10:17], v[194:201], v[154:157], v192, v192 op_sel_hi:[0,0,0]
	s_nop 1
	v_mfma_scale_f32_16x16x128_f8f6f4 v[142:145], v[2:9], v[202:209], v[142:145], v192, v192 op_sel_hi:[0,0,0]
	s_nop 1
	v_mfma_scale_f32_16x16x128_f8f6f4 v[138:141], v[10:17], v[202:209], v[138:141], v192, v192 op_sel_hi:[0,0,0]
	s_nop 1
	v_mfma_scale_f32_16x16x128_f8f6f4 v[126:129], v[2:9], v[210:217], v[126:129], v192, v192 op_sel_hi:[0,0,0]
	s_nop 1
	v_mfma_scale_f32_16x16x128_f8f6f4 v[122:125], v[10:17], v[210:217], v[122:125], v192, v192 op_sel_hi:[0,0,0]
	s_nop 1
	v_mfma_scale_f32_16x16x128_f8f6f4 v[110:113], v[2:9], v[218:225], v[110:113], v192, v192 op_sel_hi:[0,0,0]
	s_nop 1
	v_mfma_scale_f32_16x16x128_f8f6f4 v[106:109], v[10:17], v[218:225], v[106:109], v192, v192 op_sel_hi:[0,0,0]
	s_setprio 0
	s_setprio 1
	s_nop 1
	v_mfma_scale_f32_16x16x128_f8f6f4 v[150:153], v[18:25], v[194:201], v[150:153], v192, v192 op_sel_hi:[0,0,0]
	s_nop 1
	v_mfma_scale_f32_16x16x128_f8f6f4 v[146:149], v[26:33], v[194:201], v[146:149], v192, v192 op_sel_hi:[0,0,0]
	s_nop 1
	v_mfma_scale_f32_16x16x128_f8f6f4 v[134:137], v[18:25], v[202:209], v[134:137], v192, v192 op_sel_hi:[0,0,0]
	s_nop 1
	v_mfma_scale_f32_16x16x128_f8f6f4 v[130:133], v[26:33], v[202:209], v[130:133], v192, v192 op_sel_hi:[0,0,0]
	s_nop 1
	v_mfma_scale_f32_16x16x128_f8f6f4 v[118:121], v[18:25], v[210:217], v[118:121], v192, v192 op_sel_hi:[0,0,0]
	s_nop 1
	v_mfma_scale_f32_16x16x128_f8f6f4 v[114:117], v[26:33], v[210:217], v[114:117], v192, v192 op_sel_hi:[0,0,0]
	s_nop 1
	v_mfma_scale_f32_16x16x128_f8f6f4 v[102:105], v[18:25], v[218:225], v[102:105], v192, v192 op_sel_hi:[0,0,0]
	s_nop 1
	v_mfma_scale_f32_16x16x128_f8f6f4 v[98:101], v[26:33], v[218:225], v[98:101], v192, v192 op_sel_hi:[0,0,0]
	s_setprio 0
	s_barrier
	s_add_i32 s44, s44, s49
	v_lshl_add_u64 v[178:179], v[178:179], 0, s[14:15]
	s_mov_b32 m0, s44
	ds_read_b128 v[194:197], v191 offset:49152
	ds_read_b128 v[198:201], v191 offset:50176
	ds_read_b128 v[202:205], v191 offset:51200
	ds_read_b128 v[206:209], v191 offset:52224
	ds_read_b128 v[210:213], v191 offset:53248
	ds_read_b128 v[214:217], v191 offset:54272
	ds_read_b128 v[218:221], v191 offset:55296
	ds_read_b128 v[222:225], v191 offset:56320
	global_load_lds_dwordx4 v[178:179], off
	s_add_i32 m0, s44, 0x2000
	s_add_u32 s42, s42, 0x20080
	v_lshl_add_u64 v[178:179], v[180:181], 0, s[14:15]
	s_addc_u32 s43, s43, 0
	s_add_i32 s44, s45, s49
	global_load_lds_dwordx4 v[178:179], off
	v_lshl_add_u64 v[178:179], s[42:43], 0, v[166:167]
	s_mov_b32 m0, s44
	s_nop 0
	global_load_lds_dwordx4 v[178:179], off
	v_lshl_add_u64 v[178:179], s[42:43], 0, v[162:163]
	s_add_i32 m0, s44, 0x2000
	s_nop 0
	global_load_lds_dwordx4 v[178:179], off
	v_lshl_add_u64 v[178:179], v[182:183], 0, s[14:15]
	s_mov_b32 m0, s57
	s_nop 0
	global_load_lds_dwordx4 v[178:179], off
	v_lshl_add_u64 v[178:179], v[184:185], 0, s[14:15]
	s_mov_b32 m0, s58
	s_nop 0
	global_load_lds_dwordx4 v[178:179], off
	s_waitcnt vmcnt(8)
	s_waitcnt lgkmcnt(0)
	s_barrier
	s_setprio 1
	s_waitcnt lgkmcnt(0)
	s_nop 1
	v_mfma_scale_f32_16x16x128_f8f6f4 v[94:97], v[2:9], v[194:201], v[94:97], v192, v192 op_sel_hi:[0,0,0]
	s_nop 1
	v_mfma_scale_f32_16x16x128_f8f6f4 v[90:93], v[10:17], v[194:201], v[90:93], v192, v192 op_sel_hi:[0,0,0]
	s_nop 1
	v_mfma_scale_f32_16x16x128_f8f6f4 v[78:81], v[2:9], v[202:209], v[78:81], v192, v192 op_sel_hi:[0,0,0]
	s_nop 1
	v_mfma_scale_f32_16x16x128_f8f6f4 v[74:77], v[10:17], v[202:209], v[74:77], v192, v192 op_sel_hi:[0,0,0]
	s_nop 1
	v_mfma_scale_f32_16x16x128_f8f6f4 v[62:65], v[2:9], v[210:217], v[62:65], v192, v192 op_sel_hi:[0,0,0]
	s_nop 1
	v_mfma_scale_f32_16x16x128_f8f6f4 v[58:61], v[10:17], v[210:217], v[58:61], v192, v192 op_sel_hi:[0,0,0]
	s_nop 1
	v_mfma_scale_f32_16x16x128_f8f6f4 v[46:49], v[2:9], v[218:225], v[46:49], v192, v192 op_sel_hi:[0,0,0]
	s_nop 1
	v_mfma_scale_f32_16x16x128_f8f6f4 v[42:45], v[10:17], v[218:225], v[42:45], v192, v192 op_sel_hi:[0,0,0]
	s_setprio 0
	s_setprio 1
	s_nop 1
	v_mfma_scale_f32_16x16x128_f8f6f4 v[86:89], v[18:25], v[194:201], v[86:89], v192, v192 op_sel_hi:[0,0,0]
	s_nop 1
	v_mfma_scale_f32_16x16x128_f8f6f4 v[82:85], v[26:33], v[194:201], v[82:85], v192, v192 op_sel_hi:[0,0,0]
	s_nop 1
	v_mfma_scale_f32_16x16x128_f8f6f4 v[70:73], v[18:25], v[202:209], v[70:73], v192, v192 op_sel_hi:[0,0,0]
	s_nop 1
	v_mfma_scale_f32_16x16x128_f8f6f4 v[66:69], v[26:33], v[202:209], v[66:69], v192, v192 op_sel_hi:[0,0,0]
	s_nop 1
	v_mfma_scale_f32_16x16x128_f8f6f4 v[54:57], v[18:25], v[210:217], v[54:57], v192, v192 op_sel_hi:[0,0,0]
	s_nop 1
	v_mfma_scale_f32_16x16x128_f8f6f4 v[50:53], v[26:33], v[210:217], v[50:53], v192, v192 op_sel_hi:[0,0,0]
	s_nop 1
	v_mfma_scale_f32_16x16x128_f8f6f4 v[38:41], v[18:25], v[218:225], v[38:41], v192, v192 op_sel_hi:[0,0,0]
	s_nop 1
	v_mfma_scale_f32_16x16x128_f8f6f4 v[34:37], v[26:33], v[218:225], v[34:37], v192, v192 op_sel_hi:[0,0,0]
	s_add_i32 s68, s68, 2
	s_add_u32 s40, s40, 0x100
	s_addc_u32 s41, s41, 0
	s_add_u32 s66, s66, 0x100
	s_addc_u32 s67, s67, 0
	s_cmp_lt_u32 s68, 6
	s_setprio 0
	s_barrier
	s_cbranch_scc1 .LBB0_394
	s_nop 15
	s_nop 15
	s_andn2_b64 vcc, exec, s[16:17]
	s_cbranch_vccnz .LBB0_397
	s_barrier

.LBB0_786:
	ds_read_b128 v[20:23], v196
	ds_read_b128 v[166:169], v196 offset:1024
	ds_read_b128 v[14:17], v196 offset:2048
	ds_read_b128 v[162:165], v196 offset:3072
	ds_read_b128 v[8:11], v197
	ds_read_b128 v[154:157], v197 offset:1024
	ds_read_b128 v[2:5], v197 offset:2048
	ds_read_b128 v[158:161], v197 offset:3072
	s_add_u32 s44, s54, 0x1100
	s_addc_u32 s45, s55, 0
	s_cmp_eq_u32 s87, 44
	s_cselect_b32 s59, s9, s45
	s_cselect_b32 s58, s8, s44
	s_cselect_b32 s57, s53, s86
	s_cselect_b32 s56, s52, s81
	s_mov_b32 m0, s75
	v_lshl_add_u64 v[6:7], s[54:55], 0, v[178:179]
	ds_read_b128 v[186:189], v198
	ds_read_b128 v[190:193], v198 offset:1024
	ds_read_b128 v[202:205], v198 offset:2048
	ds_read_b128 v[218:221], v198 offset:3072
	ds_read_b128 v[208:211], v198 offset:4096
	ds_read_b128 v[222:225], v198 offset:5120
	ds_read_b128 v[214:217], v198 offset:6144
	ds_read_b128 v[226:229], v198 offset:7168
	global_load_lds_dwordx4 v[6:7], off
	v_lshl_add_u64 v[6:7], s[54:55], 0, v[180:181]
	s_mov_b32 m0, s76
	s_nop 0
	global_load_lds_dwordx4 v[6:7], off
	s_waitcnt vmcnt(8)
	s_waitcnt lgkmcnt(0)
	s_barrier
	s_setprio 1
	s_waitcnt lgkmcnt(0)
	v_mov_b32_e32 v24, v166
	v_mov_b32_e32 v25, v167
	s_nop 1
	v_mfma_scale_f32_16x16x128_f8f6f4 v[150:153], v[20:25], v[186:191], v[150:153], v168, v192 op_sel_hi:[0,0,0] cbsz:2 blgp:2
	v_mov_b32_e32 v18, v162
	v_mov_b32_e32 v19, v163
	s_nop 1
	v_mfma_scale_f32_16x16x128_f8f6f4 v[146:149], v[14:19], v[186:191], v[146:149], v164, v192 op_sel_hi:[0,0,0] cbsz:2 blgp:2
	v_mov_b32_e32 v206, v218
	v_mov_b32_e32 v207, v219
	s_nop 1
	v_mfma_scale_f32_16x16x128_f8f6f4 v[142:145], v[20:25], v[202:207], v[142:145], v168, v220 op_sel_hi:[0,0,0] cbsz:2 blgp:2
	s_nop 1
	v_mfma_scale_f32_16x16x128_f8f6f4 v[138:141], v[14:19], v[202:207], v[138:141], v164, v220 op_sel_hi:[0,0,0] cbsz:2 blgp:2
	v_mov_b32_e32 v212, v222
	v_mov_b32_e32 v213, v223
	s_nop 1
	v_mfma_scale_f32_16x16x128_f8f6f4 v[134:137], v[20:25], v[208:213], v[134:137], v168, v224 op_sel_hi:[0,0,0] cbsz:2 blgp:2
	s_nop 1
	v_mfma_scale_f32_16x16x128_f8f6f4 v[122:125], v[14:19], v[208:213], v[122:125], v164, v224 op_sel_hi:[0,0,0] cbsz:2 blgp:2
	v_mov_b32_e32 v218, v226
	v_mov_b32_e32 v219, v227
	s_nop 1
	v_mfma_scale_f32_16x16x128_f8f6f4 v[106:109], v[20:25], v[214:219], v[106:109], v168, v228 op_sel_hi:[0,0,0] cbsz:2 blgp:2
	s_nop 1
	v_mfma_scale_f32_16x16x128_f8f6f4 v[98:101], v[14:19], v[214:219], v[98:101], v164, v228 op_sel_hi:[0,0,0] cbsz:2 blgp:2
	s_setprio 0
	s_setprio 1
	v_mov_b32_e32 v12, v154
	v_mov_b32_e32 v13, v155
	s_nop 1
	v_mfma_scale_f32_16x16x128_f8f6f4 v[130:133], v[8:13], v[186:191], v[130:133], v156, v192 op_sel_hi:[0,0,0] cbsz:2 blgp:2
	v_mov_b32_e32 v6, v158
	v_mov_b32_e32 v7, v159
	s_nop 1
	v_mfma_scale_f32_16x16x128_f8f6f4 v[126:129], v[2:7], v[186:191], v[126:129], v160, v192 op_sel_hi:[0,0,0] cbsz:2 blgp:2
	s_nop 1
	v_mfma_scale_f32_16x16x128_f8f6f4 v[118:121], v[8:13], v[202:207], v[118:121], v156, v220 op_sel_hi:[0,0,0] cbsz:2 blgp:2
	s_nop 1
	v_mfma_scale_f32_16x16x128_f8f6f4 v[114:117], v[2:7], v[202:207], v[114:117], v160, v220 op_sel_hi:[0,0,0] cbsz:2 blgp:2
	s_nop 1
	v_mfma_scale_f32_16x16x128_f8f6f4 v[110:113], v[8:13], v[208:213], v[110:113], v156, v224 op_sel_hi:[0,0,0] cbsz:2 blgp:2
	s_nop 1
	v_mfma_scale_f32_16x16x128_f8f6f4 v[102:105], v[2:7], v[208:213], v[102:105], v160, v224 op_sel_hi:[0,0,0] cbsz:2 blgp:2
	s_nop 1
	v_mfma_scale_f32_16x16x128_f8f6f4 v[94:97], v[8:13], v[214:219], v[94:97], v156, v228 op_sel_hi:[0,0,0] cbsz:2 blgp:2
	s_nop 1
	v_mfma_scale_f32_16x16x128_f8f6f4 v[90:93], v[2:7], v[214:219], v[90:93], v160, v228 op_sel_hi:[0,0,0] cbsz:2 blgp:2
	s_setprio 0
	s_barrier
	s_mov_b32 m0, s77
	v_lshl_add_u64 v[186:187], s[56:57], 0, v[172:173]
	s_add_u32 s44, s56, 0xc0000
	ds_read_b128 v[202:205], v198 offset:16384
	ds_read_b128 v[224:227], v198 offset:17408
	ds_read_b128 v[208:211], v198 offset:18432
	ds_read_b128 v[228:231], v198 offset:19456
	ds_read_b128 v[214:217], v198 offset:20480
	ds_read_b128 v[232:235], v198 offset:21504
	ds_read_b128 v[220:223], v198 offset:22528
	ds_read_b128 v[236:239], v198 offset:23552
	global_load_lds_dwordx4 v[186:187], off
	v_lshl_add_u64 v[188:189], s[56:57], 0, v[170:171]
	s_mov_b32 m0, s78
	s_addc_u32 s45, s57, 0
	global_load_lds_dwordx4 v[188:189], off
	v_lshl_add_u64 v[154:155], s[44:45], 0, v[172:173]
	s_mov_b32 m0, s79
	v_lshl_add_u64 v[190:191], s[58:59], 0, v[172:173]
	global_load_lds_dwordx4 v[154:155], off
	v_lshl_add_u64 v[154:155], s[44:45], 0, v[170:171]
	s_mov_b32 m0, s80
	v_lshl_add_u64 v[192:193], s[58:59], 0, v[170:171]
	global_load_lds_dwordx4 v[154:155], off
	s_mov_b32 m0, s49
	s_nop 0
	global_load_lds_dwordx4 v[190:191], off
	s_mov_b32 m0, s60
	s_nop 0
	global_load_lds_dwordx4 v[192:193], off
	s_waitcnt vmcnt(8)
	s_waitcnt lgkmcnt(0)
	s_barrier
	s_setprio 1
	s_waitcnt lgkmcnt(0)
	v_mov_b32_e32 v206, v224
	v_mov_b32_e32 v207, v225
	s_nop 1
	v_mfma_scale_f32_16x16x128_f8f6f4 v[86:89], v[20:25], v[202:207], v[86:89], v168, v226 op_sel_hi:[0,0,0] cbsz:2 blgp:2
	s_nop 1
	v_mfma_scale_f32_16x16x128_f8f6f4 v[82:85], v[14:19], v[202:207], v[82:85], v164, v226 op_sel_hi:[0,0,0] cbsz:2 blgp:2
	v_mov_b32_e32 v212, v228
	v_mov_b32_e32 v213, v229
	s_nop 1
	v_mfma_scale_f32_16x16x128_f8f6f4 v[78:81], v[20:25], v[208:213], v[78:81], v168, v230 op_sel_hi:[0,0,0] cbsz:2 blgp:2
	s_nop 1
	v_mfma_scale_f32_16x16x128_f8f6f4 v[74:77], v[14:19], v[208:213], v[74:77], v164, v230 op_sel_hi:[0,0,0] cbsz:2 blgp:2
	v_mov_b32_e32 v218, v232
	v_mov_b32_e32 v219, v233
	s_nop 1
	v_mfma_scale_f32_16x16x128_f8f6f4 v[70:73], v[20:25], v[214:219], v[70:73], v168, v234 op_sel_hi:[0,0,0] cbsz:2 blgp:2
	s_nop 1
	v_mfma_scale_f32_16x16x128_f8f6f4 v[58:61], v[14:19], v[214:219], v[58:61], v164, v234 op_sel_hi:[0,0,0] cbsz:2 blgp:2
	v_mov_b32_e32 v224, v236
	v_mov_b32_e32 v225, v237
	s_nop 1
	v_mfma_scale_f32_16x16x128_f8f6f4 v[42:45], v[20:25], v[220:225], v[42:45], v168, v238 op_sel_hi:[0,0,0] cbsz:2 blgp:2
	s_nop 1
	v_mfma_scale_f32_16x16x128_f8f6f4 v[34:37], v[14:19], v[220:225], v[34:37], v164, v238 op_sel_hi:[0,0,0] cbsz:2 blgp:2
	s_setprio 0
	s_setprio 1
	s_nop 1
	v_mfma_scale_f32_16x16x128_f8f6f4 v[66:69], v[8:13], v[202:207], v[66:69], v156, v226 op_sel_hi:[0,0,0] cbsz:2 blgp:2
	s_nop 1
	v_mfma_scale_f32_16x16x128_f8f6f4 v[62:65], v[2:7], v[202:207], v[62:65], v160, v226 op_sel_hi:[0,0,0] cbsz:2 blgp:2
	s_nop 1
	v_mfma_scale_f32_16x16x128_f8f6f4 v[54:57], v[8:13], v[208:213], v[54:57], v156, v230 op_sel_hi:[0,0,0] cbsz:2 blgp:2
	s_nop 1
	v_mfma_scale_f32_16x16x128_f8f6f4 v[50:53], v[2:7], v[208:213], v[50:53], v160, v230 op_sel_hi:[0,0,0] cbsz:2 blgp:2
	s_nop 1
	v_mfma_scale_f32_16x16x128_f8f6f4 v[46:49], v[8:13], v[214:219], v[46:49], v156, v234 op_sel_hi:[0,0,0] cbsz:2 blgp:2
	s_nop 1
	v_mfma_scale_f32_16x16x128_f8f6f4 v[38:41], v[2:7], v[214:219], v[38:41], v160, v234 op_sel_hi:[0,0,0] cbsz:2 blgp:2
	s_nop 1
	v_mfma_scale_f32_16x16x128_f8f6f4 v[30:33], v[8:13], v[220:225], v[30:33], v156, v238 op_sel_hi:[0,0,0] cbsz:2 blgp:2
	s_nop 1
	v_mfma_scale_f32_16x16x128_f8f6f4 v[26:29], v[2:7], v[220:225], v[26:29], v160, v238 op_sel_hi:[0,0,0] cbsz:2 blgp:2
	s_setprio 0
	s_barrier
	ds_read_b128 v[20:23], v199
	ds_read_b128 v[166:169], v199 offset:1024
	ds_read_b128 v[14:17], v199 offset:2048
	ds_read_b128 v[162:165], v199 offset:3072
	ds_read_b128 v[8:11], v200
	ds_read_b128 v[158:161], v200 offset:1024
	ds_read_b128 v[2:5], v200 offset:2048
	ds_read_b128 v[154:157], v200 offset:3072
	s_add_u32 s44, s58, 0xc0000
	s_addc_u32 s45, s59, 0
	s_mov_b32 m0, s61
	v_lshl_add_u64 v[6:7], s[44:45], 0, v[172:173]
	ds_read_b128 v[202:205], v198 offset:32768
	ds_read_b128 v[224:227], v198 offset:33792
	ds_read_b128 v[208:211], v198 offset:34816
	ds_read_b128 v[228:231], v198 offset:35840
	ds_read_b128 v[214:217], v198 offset:36864
	ds_read_b128 v[232:235], v198 offset:37888
	ds_read_b128 v[220:223], v198 offset:38912
	ds_read_b128 v[236:239], v198 offset:39936
	global_load_lds_dwordx4 v[6:7], off
	v_lshl_add_u64 v[6:7], s[44:45], 0, v[170:171]
	s_mov_b32 m0, s62
	s_nop 0
	global_load_lds_dwordx4 v[6:7], off
	s_waitcnt vmcnt(8)
	s_waitcnt lgkmcnt(0)
	s_barrier
	s_setprio 1
	s_waitcnt lgkmcnt(0)
	v_mov_b32_e32 v206, v224
	v_mov_b32_e32 v207, v225
	v_mov_b32_e32 v24, v166
	v_mov_b32_e32 v25, v167
	s_nop 1
	v_mfma_scale_f32_16x16x128_f8f6f4 v[150:153], v[20:25], v[202:207], v[150:153], v168, v226 op_sel_hi:[0,0,0] cbsz:2 blgp:2
	v_mov_b32_e32 v18, v162
	v_mov_b32_e32 v19, v163
	s_nop 1
	v_mfma_scale_f32_16x16x128_f8f6f4 v[146:149], v[14:19], v[202:207], v[146:149], v164, v226 op_sel_hi:[0,0,0] cbsz:2 blgp:2
	v_mov_b32_e32 v212, v228
	v_mov_b32_e32 v213, v229
	s_nop 1
	v_mfma_scale_f32_16x16x128_f8f6f4 v[142:145], v[20:25], v[208:213], v[142:145], v168, v230 op_sel_hi:[0,0,0] cbsz:2 blgp:2
	s_nop 1
	v_mfma_scale_f32_16x16x128_f8f6f4 v[138:141], v[14:19], v[208:213], v[138:141], v164, v230 op_sel_hi:[0,0,0] cbsz:2 blgp:2
	v_mov_b32_e32 v218, v232
	v_mov_b32_e32 v219, v233
	s_nop 1
	v_mfma_scale_f32_16x16x128_f8f6f4 v[134:137], v[20:25], v[214:219], v[134:137], v168, v234 op_sel_hi:[0,0,0] cbsz:2 blgp:2
	s_nop 1
	v_mfma_scale_f32_16x16x128_f8f6f4 v[122:125], v[14:19], v[214:219], v[122:125], v164, v234 op_sel_hi:[0,0,0] cbsz:2 blgp:2
	v_mov_b32_e32 v224, v236
	v_mov_b32_e32 v225, v237
	s_nop 1
	v_mfma_scale_f32_16x16x128_f8f6f4 v[106:109], v[20:25], v[220:225], v[106:109], v168, v238 op_sel_hi:[0,0,0] cbsz:2 blgp:2
	s_nop 1
	v_mfma_scale_f32_16x16x128_f8f6f4 v[98:101], v[14:19], v[220:225], v[98:101], v164, v238 op_sel_hi:[0,0,0] cbsz:2 blgp:2
	s_setprio 0
	s_setprio 1
	v_mov_b32_e32 v12, v158
	v_mov_b32_e32 v13, v159
	s_nop 1
	v_mfma_scale_f32_16x16x128_f8f6f4 v[130:133], v[8:13], v[202:207], v[130:133], v160, v226 op_sel_hi:[0,0,0] cbsz:2 blgp:2
	v_mov_b32_e32 v6, v154
	v_mov_b32_e32 v7, v155
	s_nop 1
	v_mfma_scale_f32_16x16x128_f8f6f4 v[126:129], v[2:7], v[202:207], v[126:129], v156, v226 op_sel_hi:[0,0,0] cbsz:2 blgp:2
	s_nop 1
	v_mfma_scale_f32_16x16x128_f8f6f4 v[118:121], v[8:13], v[208:213], v[118:121], v160, v230 op_sel_hi:[0,0,0] cbsz:2 blgp:2
	s_nop 1
	v_mfma_scale_f32_16x16x128_f8f6f4 v[114:117], v[2:7], v[208:213], v[114:117], v156, v230 op_sel_hi:[0,0,0] cbsz:2 blgp:2
	s_nop 1
	v_mfma_scale_f32_16x16x128_f8f6f4 v[110:113], v[8:13], v[214:219], v[110:113], v160, v234 op_sel_hi:[0,0,0] cbsz:2 blgp:2
	s_nop 1
	v_mfma_scale_f32_16x16x128_f8f6f4 v[102:105], v[2:7], v[214:219], v[102:105], v156, v234 op_sel_hi:[0,0,0] cbsz:2 blgp:2
	s_nop 1
	v_mfma_scale_f32_16x16x128_f8f6f4 v[94:97], v[8:13], v[220:225], v[94:97], v160, v238 op_sel_hi:[0,0,0] cbsz:2 blgp:2
	s_nop 1
	v_mfma_scale_f32_16x16x128_f8f6f4 v[90:93], v[2:7], v[220:225], v[90:93], v156, v238 op_sel_hi:[0,0,0] cbsz:2 blgp:2
	s_setprio 0
	s_barrier
	s_mov_b32 m0, s82
	v_lshl_add_u64 v[154:155], v[186:187], 0, s[14:15]
	s_add_u32 s44, s56, 0xc0080
	ds_read_b128 v[202:205], v198 offset:49152
	ds_read_b128 v[224:227], v198 offset:50176
	ds_read_b128 v[208:211], v198 offset:51200
	ds_read_b128 v[228:231], v198 offset:52224
	ds_read_b128 v[214:217], v198 offset:53248
	ds_read_b128 v[232:235], v198 offset:54272
	ds_read_b128 v[220:223], v198 offset:55296
	ds_read_b128 v[236:239], v198 offset:56320
	global_load_lds_dwordx4 v[154:155], off
	v_lshl_add_u64 v[154:155], v[188:189], 0, s[14:15]
	s_mov_b32 m0, s83
	s_addc_u32 s45, s57, 0
	global_load_lds_dwordx4 v[154:155], off
	v_lshl_add_u64 v[154:155], s[44:45], 0, v[172:173]
	s_mov_b32 m0, s84
	s_nop 0
	global_load_lds_dwordx4 v[154:155], off
	v_lshl_add_u64 v[154:155], s[44:45], 0, v[170:171]
	s_mov_b32 m0, s85
	s_nop 0
	global_load_lds_dwordx4 v[154:155], off
	v_lshl_add_u64 v[154:155], v[190:191], 0, s[14:15]
	s_mov_b32 m0, s67
	s_nop 0
	global_load_lds_dwordx4 v[154:155], off
	v_lshl_add_u64 v[154:155], v[192:193], 0, s[14:15]
	s_mov_b32 m0, s68
	s_nop 0
	global_load_lds_dwordx4 v[154:155], off
	s_waitcnt vmcnt(8)
	s_waitcnt lgkmcnt(0)
	s_barrier
	s_setprio 1
	s_waitcnt lgkmcnt(0)
	v_mov_b32_e32 v206, v224
	v_mov_b32_e32 v207, v225
	s_nop 1
	v_mfma_scale_f32_16x16x128_f8f6f4 v[86:89], v[20:25], v[202:207], v[86:89], v168, v226 op_sel_hi:[0,0,0] cbsz:2 blgp:2
	s_nop 1
	v_mfma_scale_f32_16x16x128_f8f6f4 v[82:85], v[14:19], v[202:207], v[82:85], v164, v226 op_sel_hi:[0,0,0] cbsz:2 blgp:2
	v_mov_b32_e32 v212, v228
	v_mov_b32_e32 v213, v229
	s_nop 1
	v_mfma_scale_f32_16x16x128_f8f6f4 v[78:81], v[20:25], v[208:213], v[78:81], v168, v230 op_sel_hi:[0,0,0] cbsz:2 blgp:2
	s_nop 1
	v_mfma_scale_f32_16x16x128_f8f6f4 v[74:77], v[14:19], v[208:213], v[74:77], v164, v230 op_sel_hi:[0,0,0] cbsz:2 blgp:2
	v_mov_b32_e32 v218, v232
	v_mov_b32_e32 v219, v233
	s_nop 1
	v_mfma_scale_f32_16x16x128_f8f6f4 v[70:73], v[20:25], v[214:219], v[70:73], v168, v234 op_sel_hi:[0,0,0] cbsz:2 blgp:2
	s_nop 1
	v_mfma_scale_f32_16x16x128_f8f6f4 v[58:61], v[14:19], v[214:219], v[58:61], v164, v234 op_sel_hi:[0,0,0] cbsz:2 blgp:2
	v_mov_b32_e32 v224, v236
	v_mov_b32_e32 v225, v237
	s_nop 1
	v_mfma_scale_f32_16x16x128_f8f6f4 v[42:45], v[20:25], v[220:225], v[42:45], v168, v238 op_sel_hi:[0,0,0] cbsz:2 blgp:2
	s_nop 1
	v_mfma_scale_f32_16x16x128_f8f6f4 v[34:37], v[14:19], v[220:225], v[34:37], v164, v238 op_sel_hi:[0,0,0] cbsz:2 blgp:2
	s_setprio 0
	s_setprio 1
	s_nop 1
	v_mfma_scale_f32_16x16x128_f8f6f4 v[66:69], v[8:13], v[202:207], v[66:69], v160, v226 op_sel_hi:[0,0,0] cbsz:2 blgp:2
	s_nop 1
	v_mfma_scale_f32_16x16x128_f8f6f4 v[62:65], v[2:7], v[202:207], v[62:65], v156, v226 op_sel_hi:[0,0,0] cbsz:2 blgp:2
	s_nop 1
	v_mfma_scale_f32_16x16x128_f8f6f4 v[54:57], v[8:13], v[208:213], v[54:57], v160, v230 op_sel_hi:[0,0,0] cbsz:2 blgp:2
	s_nop 1
	v_mfma_scale_f32_16x16x128_f8f6f4 v[50:53], v[2:7], v[208:213], v[50:53], v156, v230 op_sel_hi:[0,0,0] cbsz:2 blgp:2
	s_nop 1
	v_mfma_scale_f32_16x16x128_f8f6f4 v[46:49], v[8:13], v[214:219], v[46:49], v160, v234 op_sel_hi:[0,0,0] cbsz:2 blgp:2
	s_nop 1
	v_mfma_scale_f32_16x16x128_f8f6f4 v[38:41], v[2:7], v[214:219], v[38:41], v156, v234 op_sel_hi:[0,0,0] cbsz:2 blgp:2
	s_nop 1
	v_mfma_scale_f32_16x16x128_f8f6f4 v[30:33], v[8:13], v[220:225], v[30:33], v160, v238 op_sel_hi:[0,0,0] cbsz:2 blgp:2
	s_nop 1
	v_mfma_scale_f32_16x16x128_f8f6f4 v[26:29], v[2:7], v[220:225], v[26:29], v156, v238 op_sel_hi:[0,0,0] cbsz:2 blgp:2
	s_add_i32 s87, s87, 2
	s_add_u32 s54, s54, 0x100
	s_addc_u32 s55, s55, 0
	s_add_u32 s81, s81, 0x100
	s_addc_u32 s86, s86, 0
	s_cmp_lt_u32 s87, 46
	s_setprio 0
	s_barrier
	s_cbranch_scc1 .LBB0_786
	s_nop 15
	s_nop 15
	s_andn2_b64 vcc, exec, s[20:21]
	s_cbranch_vccnz .LBB0_789
	s_barrier

.LBB0_944:
	ds_read_b128 v[20:23], v196
	ds_read_b128 v[166:169], v196 offset:1024
	ds_read_b128 v[14:17], v196 offset:2048
	ds_read_b128 v[162:165], v196 offset:3072
	ds_read_b128 v[8:11], v197
	ds_read_b128 v[158:161], v197 offset:1024
	ds_read_b128 v[2:5], v197 offset:2048
	ds_read_b128 v[154:157], v197 offset:3072
	s_add_u32 s40, s38, 0xfff80080
	s_addc_u32 s41, s39, -1
	s_cmp_eq_u32 s64, 28
	s_cselect_b32 s43, s23, s41
	s_cselect_b32 s42, s60, s40
	s_cselect_b32 s41, s21, s63
	s_cselect_b32 s40, s61, s62
	s_add_u32 s94, s38, 0xfff80000
	s_addc_u32 s95, s39, -1
	ds_read_b128 v[186:189], v198
	ds_read_b128 v[190:193], v198 offset:1024
	ds_read_b128 v[200:203], v198 offset:2048
	ds_read_b128 v[216:219], v198 offset:3072
	ds_read_b128 v[206:209], v198 offset:4096
	ds_read_b128 v[220:223], v198 offset:5120
	ds_read_b128 v[212:215], v198 offset:6144
	ds_read_b128 v[224:227], v198 offset:7168
	v_lshl_add_u64 v[238:239], s[94:95], 0, v[178:179]
	v_lshl_add_u64 v[240:241], s[94:95], 0, v[180:181]
	v_lshl_add_u64 v[242:243], s[38:39], 0, v[178:179]
	v_lshl_add_u64 v[244:245], s[38:39], 0, v[180:181]
	s_waitcnt vmcnt(4)
	s_waitcnt lgkmcnt(0)
	s_barrier
	s_setprio 1
	s_waitcnt lgkmcnt(0)
	v_mov_b32_e32 v24, v166
	v_mov_b32_e32 v25, v167
	s_nop 1
	v_mfma_scale_f32_16x16x128_f8f6f4 v[150:153], v[20:25], v[186:191], v[150:153], v168, v192 op_sel_hi:[0,0,0] cbsz:2 blgp:2
	s_mov_b32 m0, s53
	s_nop 0
	global_load_lds_dwordx4 v[238:239], off
	v_mov_b32_e32 v18, v162
	v_mov_b32_e32 v19, v163
	s_nop 1
	v_mfma_scale_f32_16x16x128_f8f6f4 v[146:149], v[14:19], v[186:191], v[146:149], v164, v192 op_sel_hi:[0,0,0] cbsz:2 blgp:2
	v_mov_b32_e32 v204, v216
	v_mov_b32_e32 v205, v217
	s_nop 1
	v_mfma_scale_f32_16x16x128_f8f6f4 v[142:145], v[20:25], v[200:205], v[142:145], v168, v218 op_sel_hi:[0,0,0] cbsz:2 blgp:2
	s_nop 1
	v_mfma_scale_f32_16x16x128_f8f6f4 v[138:141], v[14:19], v[200:205], v[138:141], v164, v218 op_sel_hi:[0,0,0] cbsz:2 blgp:2
	v_mov_b32_e32 v210, v220
	v_mov_b32_e32 v211, v221
	s_nop 1
	v_mfma_scale_f32_16x16x128_f8f6f4 v[134:137], v[20:25], v[206:211], v[134:137], v168, v222 op_sel_hi:[0,0,0] cbsz:2 blgp:2
	s_mov_b32 m0, s54
	s_nop 0
	global_load_lds_dwordx4 v[240:241], off
	s_nop 1
	v_mfma_scale_f32_16x16x128_f8f6f4 v[130:133], v[14:19], v[206:211], v[130:133], v164, v222 op_sel_hi:[0,0,0] cbsz:2 blgp:2
	v_mov_b32_e32 v216, v224
	v_mov_b32_e32 v217, v225
	s_nop 1
	v_mfma_scale_f32_16x16x128_f8f6f4 v[126:129], v[20:25], v[212:217], v[126:129], v168, v226 op_sel_hi:[0,0,0] cbsz:2 blgp:2
	s_nop 1
	v_mfma_scale_f32_16x16x128_f8f6f4 v[122:125], v[14:19], v[212:217], v[122:125], v164, v226 op_sel_hi:[0,0,0] cbsz:2 blgp:2
	s_setprio 0
	s_setprio 1
	v_mov_b32_e32 v12, v158
	v_mov_b32_e32 v13, v159
	s_nop 1
	v_mfma_scale_f32_16x16x128_f8f6f4 v[118:121], v[8:13], v[186:191], v[118:121], v160, v192 op_sel_hi:[0,0,0] cbsz:2 blgp:2
	s_add_i32 m0, s37, 0xc000
	s_nop 0
	global_load_lds_dwordx4 v[242:243], off
	v_mov_b32_e32 v6, v154
	v_mov_b32_e32 v7, v155
	s_nop 1
	v_mfma_scale_f32_16x16x128_f8f6f4 v[114:117], v[2:7], v[186:191], v[114:117], v156, v192 op_sel_hi:[0,0,0] cbsz:2 blgp:2
	s_nop 1
	v_mfma_scale_f32_16x16x128_f8f6f4 v[110:113], v[8:13], v[200:205], v[110:113], v160, v218 op_sel_hi:[0,0,0] cbsz:2 blgp:2
	s_nop 1
	v_mfma_scale_f32_16x16x128_f8f6f4 v[106:109], v[2:7], v[200:205], v[106:109], v156, v218 op_sel_hi:[0,0,0] cbsz:2 blgp:2
	s_nop 1
	v_mfma_scale_f32_16x16x128_f8f6f4 v[102:105], v[8:13], v[206:211], v[102:105], v160, v222 op_sel_hi:[0,0,0] cbsz:2 blgp:2
	s_add_i32 m0, s37, 0xe000
	s_nop 0
	global_load_lds_dwordx4 v[244:245], off
	s_nop 1
	v_mfma_scale_f32_16x16x128_f8f6f4 v[98:101], v[2:7], v[206:211], v[98:101], v156, v222 op_sel_hi:[0,0,0] cbsz:2 blgp:2
	s_nop 1
	v_mfma_scale_f32_16x16x128_f8f6f4 v[94:97], v[8:13], v[212:217], v[94:97], v160, v226 op_sel_hi:[0,0,0] cbsz:2 blgp:2
	s_nop 1
	v_mfma_scale_f32_16x16x128_f8f6f4 v[90:93], v[2:7], v[212:217], v[90:93], v156, v226 op_sel_hi:[0,0,0] cbsz:2 blgp:2
	s_setprio 0
	s_barrier
	s_add_u32 s44, s40, 0x80000
	s_addc_u32 s45, s41, 0
	ds_read_b128 v[200:203], v198 offset:16384
	ds_read_b128 v[222:225], v198 offset:17408
	ds_read_b128 v[206:209], v198 offset:18432
	ds_read_b128 v[226:229], v198 offset:19456
	ds_read_b128 v[212:215], v198 offset:20480
	ds_read_b128 v[230:233], v198 offset:21504
	ds_read_b128 v[218:221], v198 offset:22528
	ds_read_b128 v[234:237], v198 offset:23552
	v_lshl_add_u64 v[186:187], s[40:41], 0, v[174:175]
	v_lshl_add_u64 v[188:189], s[40:41], 0, v[170:171]
	v_lshl_add_u64 v[190:191], s[42:43], 0, v[176:177]
	v_lshl_add_u64 v[192:193], s[42:43], 0, v[172:173]
	v_lshl_add_u64 v[238:239], s[44:45], 0, v[174:175]
	v_lshl_add_u64 v[240:241], s[44:45], 0, v[170:171]
	s_waitcnt vmcnt(2)
	s_waitcnt lgkmcnt(0)
	s_barrier
	s_setprio 1
	s_waitcnt lgkmcnt(0)
	v_mov_b32_e32 v204, v222
	v_mov_b32_e32 v205, v223
	s_nop 1
	v_mfma_scale_f32_16x16x128_f8f6f4 v[86:89], v[20:25], v[200:205], v[86:89], v168, v224 op_sel_hi:[0,0,0] cbsz:2 blgp:2
	s_add_i32 m0, s37, 0x10000
	s_nop 0
	global_load_lds_dwordx4 v[186:187], off
	s_nop 1
	v_mfma_scale_f32_16x16x128_f8f6f4 v[82:85], v[14:19], v[200:205], v[82:85], v164, v224 op_sel_hi:[0,0,0] cbsz:2 blgp:2
	v_mov_b32_e32 v210, v226
	v_mov_b32_e32 v211, v227
	s_nop 1
	v_mfma_scale_f32_16x16x128_f8f6f4 v[78:81], v[20:25], v[206:211], v[78:81], v168, v228 op_sel_hi:[0,0,0] cbsz:2 blgp:2
	s_nop 1
	v_mfma_scale_f32_16x16x128_f8f6f4 v[74:77], v[14:19], v[206:211], v[74:77], v164, v228 op_sel_hi:[0,0,0] cbsz:2 blgp:2
	v_mov_b32_e32 v216, v230
	v_mov_b32_e32 v217, v231
	s_nop 1
	v_mfma_scale_f32_16x16x128_f8f6f4 v[70:73], v[20:25], v[212:217], v[70:73], v168, v232 op_sel_hi:[0,0,0] cbsz:2 blgp:2
	s_add_i32 m0, s37, 0x12000
	s_nop 0
	global_load_lds_dwordx4 v[188:189], off
	s_nop 1
	v_mfma_scale_f32_16x16x128_f8f6f4 v[66:69], v[14:19], v[212:217], v[66:69], v164, v232 op_sel_hi:[0,0,0] cbsz:2 blgp:2
	v_mov_b32_e32 v222, v234
	v_mov_b32_e32 v223, v235
	s_nop 1
	v_mfma_scale_f32_16x16x128_f8f6f4 v[62:65], v[20:25], v[218:223], v[62:65], v168, v236 op_sel_hi:[0,0,0] cbsz:2 blgp:2
	s_nop 1
	v_mfma_scale_f32_16x16x128_f8f6f4 v[58:61], v[14:19], v[218:223], v[58:61], v164, v236 op_sel_hi:[0,0,0] cbsz:2 blgp:2
	s_setprio 0
	s_setprio 1
	s_nop 1
	v_mfma_scale_f32_16x16x128_f8f6f4 v[54:57], v[8:13], v[200:205], v[54:57], v160, v224 op_sel_hi:[0,0,0] cbsz:2 blgp:2
	s_add_i32 m0, s37, 0x14000
	s_nop 0
	global_load_lds_dwordx4 v[238:239], off
	s_nop 1
	v_mfma_scale_f32_16x16x128_f8f6f4 v[50:53], v[2:7], v[200:205], v[50:53], v156, v224 op_sel_hi:[0,0,0] cbsz:2 blgp:2
	s_nop 1
	v_mfma_scale_f32_16x16x128_f8f6f4 v[46:49], v[8:13], v[206:211], v[46:49], v160, v228 op_sel_hi:[0,0,0] cbsz:2 blgp:2
	s_nop 1
	v_mfma_scale_f32_16x16x128_f8f6f4 v[42:45], v[2:7], v[206:211], v[42:45], v156, v228 op_sel_hi:[0,0,0] cbsz:2 blgp:2
	s_nop 1
	v_mfma_scale_f32_16x16x128_f8f6f4 v[38:41], v[8:13], v[212:217], v[38:41], v160, v232 op_sel_hi:[0,0,0] cbsz:2 blgp:2
	s_add_i32 m0, s37, 0x16000
	s_nop 0
	global_load_lds_dwordx4 v[240:241], off
	s_nop 1
	v_mfma_scale_f32_16x16x128_f8f6f4 v[34:37], v[2:7], v[212:217], v[34:37], v156, v232 op_sel_hi:[0,0,0] cbsz:2 blgp:2
	s_nop 1
	v_mfma_scale_f32_16x16x128_f8f6f4 v[30:33], v[8:13], v[218:223], v[30:33], v160, v236 op_sel_hi:[0,0,0] cbsz:2 blgp:2
	s_nop 1
	v_mfma_scale_f32_16x16x128_f8f6f4 v[26:29], v[2:7], v[218:223], v[26:29], v156, v236 op_sel_hi:[0,0,0] cbsz:2 blgp:2
	s_setprio 0
	s_barrier
	s_add_i32 s44, 0, 0x18000
	s_add_i32 s45, 0, 0x1c000
	v_add_u32_e32 v2, s44, v1
	v_add_u32_e32 v6, s45, v1
	ds_read_b128 v[20:23], v2
	ds_read_b128 v[166:169], v2 offset:1024
	ds_read_b128 v[14:17], v2 offset:2048
	ds_read_b128 v[162:165], v2 offset:3072
	ds_read_b128 v[8:11], v6
	ds_read_b128 v[154:157], v6 offset:1024
	ds_read_b128 v[2:5], v6 offset:2048
	ds_read_b128 v[158:161], v6 offset:3072
	s_add_u32 s42, s42, 0x80000
	s_addc_u32 s43, s43, 0
	v_lshl_add_u64 v[238:239], s[42:43], 0, v[176:177]
	ds_read_b128 v[200:203], v198 offset:32768
	ds_read_b128 v[222:225], v198 offset:33792
	ds_read_b128 v[206:209], v198 offset:34816
	ds_read_b128 v[226:229], v198 offset:35840
	ds_read_b128 v[212:215], v198 offset:36864
	ds_read_b128 v[230:233], v198 offset:37888
	ds_read_b128 v[218:221], v198 offset:38912
	ds_read_b128 v[234:237], v198 offset:39936
	v_lshl_add_u64 v[240:241], s[42:43], 0, v[172:173]
	s_waitcnt vmcnt(4)
	s_waitcnt lgkmcnt(0)
	s_barrier
	s_setprio 1
	s_waitcnt lgkmcnt(0)
	v_mov_b32_e32 v204, v222
	v_mov_b32_e32 v205, v223
	v_mov_b32_e32 v24, v166
	v_mov_b32_e32 v25, v167
	s_nop 1
	v_mfma_scale_f32_16x16x128_f8f6f4 v[150:153], v[20:25], v[200:205], v[150:153], v168, v224 op_sel_hi:[0,0,0] cbsz:2 blgp:2
	s_mov_b32 m0, s37
	s_nop 0
	global_load_lds_dwordx4 v[190:191], off
	v_mov_b32_e32 v18, v162
	v_mov_b32_e32 v19, v163
	s_nop 1
	v_mfma_scale_f32_16x16x128_f8f6f4 v[146:149], v[14:19], v[200:205], v[146:149], v164, v224 op_sel_hi:[0,0,0] cbsz:2 blgp:2
	v_mov_b32_e32 v210, v226
	v_mov_b32_e32 v211, v227
	s_nop 1
	v_mfma_scale_f32_16x16x128_f8f6f4 v[142:145], v[20:25], v[206:211], v[142:145], v168, v228 op_sel_hi:[0,0,0] cbsz:2 blgp:2
	s_nop 1
	v_mfma_scale_f32_16x16x128_f8f6f4 v[138:141], v[14:19], v[206:211], v[138:141], v164, v228 op_sel_hi:[0,0,0] cbsz:2 blgp:2
	v_mov_b32_e32 v216, v230
	v_mov_b32_e32 v217, v231
	s_nop 1
	v_mfma_scale_f32_16x16x128_f8f6f4 v[134:137], v[20:25], v[212:217], v[134:137], v168, v232 op_sel_hi:[0,0,0] cbsz:2 blgp:2
	s_mov_b32 m0, s48
	s_nop 0
	global_load_lds_dwordx4 v[192:193], off
	s_nop 1
	v_mfma_scale_f32_16x16x128_f8f6f4 v[130:133], v[14:19], v[212:217], v[130:133], v164, v232 op_sel_hi:[0,0,0] cbsz:2 blgp:2
	v_mov_b32_e32 v222, v234
	v_mov_b32_e32 v223, v235
	s_nop 1
	v_mfma_scale_f32_16x16x128_f8f6f4 v[126:129], v[20:25], v[218:223], v[126:129], v168, v236 op_sel_hi:[0,0,0] cbsz:2 blgp:2
	s_nop 1
	v_mfma_scale_f32_16x16x128_f8f6f4 v[122:125], v[14:19], v[218:223], v[122:125], v164, v236 op_sel_hi:[0,0,0] cbsz:2 blgp:2
	s_setprio 0
	s_setprio 1
	v_mov_b32_e32 v12, v154
	v_mov_b32_e32 v13, v155
	s_nop 1
	v_mfma_scale_f32_16x16x128_f8f6f4 v[118:121], v[8:13], v[200:205], v[118:121], v156, v224 op_sel_hi:[0,0,0] cbsz:2 blgp:2
	s_mov_b32 m0, s49
	s_nop 0
	global_load_lds_dwordx4 v[238:239], off
	v_mov_b32_e32 v6, v158
	v_mov_b32_e32 v7, v159
	s_nop 1
	v_mfma_scale_f32_16x16x128_f8f6f4 v[114:117], v[2:7], v[200:205], v[114:117], v160, v224 op_sel_hi:[0,0,0] cbsz:2 blgp:2
	s_nop 1
	v_mfma_scale_f32_16x16x128_f8f6f4 v[110:113], v[8:13], v[206:211], v[110:113], v156, v228 op_sel_hi:[0,0,0] cbsz:2 blgp:2
	s_nop 1
	v_mfma_scale_f32_16x16x128_f8f6f4 v[106:109], v[2:7], v[206:211], v[106:109], v160, v228 op_sel_hi:[0,0,0] cbsz:2 blgp:2
	s_nop 1
	v_mfma_scale_f32_16x16x128_f8f6f4 v[102:105], v[8:13], v[212:217], v[102:105], v156, v232 op_sel_hi:[0,0,0] cbsz:2 blgp:2
	s_mov_b32 m0, s50
	s_nop 0
	global_load_lds_dwordx4 v[240:241], off
	s_nop 1
	v_mfma_scale_f32_16x16x128_f8f6f4 v[98:101], v[2:7], v[212:217], v[98:101], v160, v232 op_sel_hi:[0,0,0] cbsz:2 blgp:2
	s_nop 1
	v_mfma_scale_f32_16x16x128_f8f6f4 v[94:97], v[8:13], v[218:223], v[94:97], v156, v236 op_sel_hi:[0,0,0] cbsz:2 blgp:2
	s_nop 1
	v_mfma_scale_f32_16x16x128_f8f6f4 v[90:93], v[2:7], v[218:223], v[90:93], v160, v236 op_sel_hi:[0,0,0] cbsz:2 blgp:2
	s_setprio 0
	s_barrier
	s_add_u32 s40, s40, 0x80080
	s_addc_u32 s41, s41, 0
	ds_read_b128 v[200:203], v198 offset:49152
	ds_read_b128 v[222:225], v198 offset:50176
	ds_read_b128 v[206:209], v198 offset:51200
	ds_read_b128 v[226:229], v198 offset:52224
	ds_read_b128 v[212:215], v198 offset:53248
	ds_read_b128 v[230:233], v198 offset:54272
	ds_read_b128 v[218:221], v198 offset:55296
	ds_read_b128 v[234:237], v198 offset:56320
	v_lshl_add_u64 v[238:239], v[186:187], 0, s[12:13]
	v_lshl_add_u64 v[240:241], v[188:189], 0, s[12:13]
	v_lshl_add_u64 v[242:243], s[40:41], 0, v[174:175]
	v_lshl_add_u64 v[244:245], s[40:41], 0, v[170:171]
	s_waitcnt vmcnt(2)
	s_waitcnt lgkmcnt(0)
	s_barrier
	s_setprio 1
	s_waitcnt lgkmcnt(0)
	v_mov_b32_e32 v204, v222
	v_mov_b32_e32 v205, v223
	s_nop 1
	v_mfma_scale_f32_16x16x128_f8f6f4 v[86:89], v[20:25], v[200:205], v[86:89], v168, v224 op_sel_hi:[0,0,0] cbsz:2 blgp:2
	s_add_i32 m0, s37, 0x18000
	s_nop 0
	global_load_lds_dwordx4 v[238:239], off
	s_nop 1
	v_mfma_scale_f32_16x16x128_f8f6f4 v[82:85], v[14:19], v[200:205], v[82:85], v164, v224 op_sel_hi:[0,0,0] cbsz:2 blgp:2
	v_mov_b32_e32 v210, v226
	v_mov_b32_e32 v211, v227
	s_nop 1
	v_mfma_scale_f32_16x16x128_f8f6f4 v[78:81], v[20:25], v[206:211], v[78:81], v168, v228 op_sel_hi:[0,0,0] cbsz:2 blgp:2
	s_nop 1
	v_mfma_scale_f32_16x16x128_f8f6f4 v[74:77], v[14:19], v[206:211], v[74:77], v164, v228 op_sel_hi:[0,0,0] cbsz:2 blgp:2
	v_mov_b32_e32 v216, v230
	v_mov_b32_e32 v217, v231
	s_nop 1
	v_mfma_scale_f32_16x16x128_f8f6f4 v[70:73], v[20:25], v[212:217], v[70:73], v168, v232 op_sel_hi:[0,0,0] cbsz:2 blgp:2
	s_add_i32 m0, s37, 0x1a000
	s_nop 0
	global_load_lds_dwordx4 v[240:241], off
	s_nop 1
	v_mfma_scale_f32_16x16x128_f8f6f4 v[66:69], v[14:19], v[212:217], v[66:69], v164, v232 op_sel_hi:[0,0,0] cbsz:2 blgp:2
	v_mov_b32_e32 v222, v234
	v_mov_b32_e32 v223, v235
	s_nop 1
	v_mfma_scale_f32_16x16x128_f8f6f4 v[62:65], v[20:25], v[218:223], v[62:65], v168, v236 op_sel_hi:[0,0,0] cbsz:2 blgp:2
	s_nop 1
	v_mfma_scale_f32_16x16x128_f8f6f4 v[58:61], v[14:19], v[218:223], v[58:61], v164, v236 op_sel_hi:[0,0,0] cbsz:2 blgp:2
	s_setprio 0
	s_setprio 1
	s_nop 1
	v_mfma_scale_f32_16x16x128_f8f6f4 v[54:57], v[8:13], v[200:205], v[54:57], v156, v224 op_sel_hi:[0,0,0] cbsz:2 blgp:2
	s_add_i32 m0, s37, 0x1c000
	s_nop 0
	global_load_lds_dwordx4 v[242:243], off
	s_nop 1
	v_mfma_scale_f32_16x16x128_f8f6f4 v[50:53], v[2:7], v[200:205], v[50:53], v160, v224 op_sel_hi:[0,0,0] cbsz:2 blgp:2
	s_nop 1
	v_mfma_scale_f32_16x16x128_f8f6f4 v[46:49], v[8:13], v[206:211], v[46:49], v156, v228 op_sel_hi:[0,0,0] cbsz:2 blgp:2
	s_nop 1
	v_mfma_scale_f32_16x16x128_f8f6f4 v[42:45], v[2:7], v[206:211], v[42:45], v160, v228 op_sel_hi:[0,0,0] cbsz:2 blgp:2
	s_nop 1
	v_mfma_scale_f32_16x16x128_f8f6f4 v[38:41], v[8:13], v[212:217], v[38:41], v156, v232 op_sel_hi:[0,0,0] cbsz:2 blgp:2
	s_add_i32 m0, s37, 0x1e000
	s_nop 0
	global_load_lds_dwordx4 v[244:245], off
	s_nop 1
	v_mfma_scale_f32_16x16x128_f8f6f4 v[34:37], v[2:7], v[212:217], v[34:37], v160, v232 op_sel_hi:[0,0,0] cbsz:2 blgp:2
	s_nop 1
	v_mfma_scale_f32_16x16x128_f8f6f4 v[30:33], v[8:13], v[218:223], v[30:33], v156, v236 op_sel_hi:[0,0,0] cbsz:2 blgp:2
	s_nop 1
	v_mfma_scale_f32_16x16x128_f8f6f4 v[26:29], v[2:7], v[218:223], v[26:29], v160, v236 op_sel_hi:[0,0,0] cbsz:2 blgp:2
	s_add_i32 s64, s64, 2
	s_add_u32 s38, s38, 0x100
	s_addc_u32 s39, s39, 0
	s_add_u32 s62, s62, 0x100
	s_addc_u32 s63, s63, 0
	s_cmp_lt_u32 s64, 30
	s_setprio 0
	s_barrier
	s_cbranch_scc1 .LBB0_944
	s_nop 15
	s_nop 15
	s_andn2_b64 vcc, exec, s[14:15]
	s_cbranch_vccnz .LBB0_947
	s_barrier

.LBB0_1019:
	ds_read_b128 v[16:19], v183
	ds_read_b128 v[20:23], v183 offset:1024
	ds_read_b128 v[24:27], v183 offset:2048
	ds_read_b128 v[28:31], v183 offset:3072
	ds_read_b128 v[0:3], v184
	ds_read_b128 v[4:7], v184 offset:1024
	ds_read_b128 v[8:11], v184 offset:2048
	ds_read_b128 v[12:15], v184 offset:3072
	s_add_u32 s38, s36, 0xffe00080
	s_addc_u32 s39, s37, -1
	s_cmpk_eq_i32 s60, 0x7c
	s_cselect_b32 s41, s25, s39
	s_cselect_b32 s40, s56, s38
	s_cselect_b32 s39, s23, s59
	s_cselect_b32 s38, s57, s58
	v_lshl_add_u64 v[212:213], s[36:37], 0, v[164:165]
	s_add_i32 m0, s31, 0xc000
	ds_read_b128 v[172:175], v185
	ds_read_b128 v[176:179], v185 offset:1024
	ds_read_b128 v[188:191], v185 offset:2048
	ds_read_b128 v[192:195], v185 offset:3072
	ds_read_b128 v[196:199], v185 offset:4096
	ds_read_b128 v[200:203], v185 offset:5120
	ds_read_b128 v[204:207], v185 offset:6144
	ds_read_b128 v[208:211], v185 offset:7168
	global_load_lds_dwordx4 v[212:213], off
	v_lshl_add_u64 v[212:213], s[36:37], 0, v[166:167]
	s_add_i32 m0, s31, 0xe000
	s_nop 0
	global_load_lds_dwordx4 v[212:213], off
	s_waitcnt vmcnt(8)
	s_waitcnt lgkmcnt(0)
	s_barrier
	s_setprio 1
	s_waitcnt lgkmcnt(0)
	s_nop 1
	v_mfma_scale_f32_16x16x128_f8f6f4 v[156:159], v[16:23], v[172:179], v[156:159], v186, v186 op_sel_hi:[0,0,0]
	s_nop 1
	v_mfma_scale_f32_16x16x128_f8f6f4 v[152:155], v[24:31], v[172:179], v[152:155], v186, v186 op_sel_hi:[0,0,0]
	s_nop 1
	v_mfma_scale_f32_16x16x128_f8f6f4 v[148:151], v[16:23], v[188:195], v[148:151], v186, v186 op_sel_hi:[0,0,0]
	s_nop 1
	v_mfma_scale_f32_16x16x128_f8f6f4 v[144:147], v[24:31], v[188:195], v[144:147], v186, v186 op_sel_hi:[0,0,0]
	s_nop 1
	v_mfma_scale_f32_16x16x128_f8f6f4 v[140:143], v[16:23], v[196:203], v[140:143], v186, v186 op_sel_hi:[0,0,0]
	s_nop 1
	v_mfma_scale_f32_16x16x128_f8f6f4 v[124:127], v[24:31], v[196:203], v[124:127], v186, v186 op_sel_hi:[0,0,0]
	s_nop 1
	v_mfma_scale_f32_16x16x128_f8f6f4 v[116:119], v[16:23], v[204:211], v[116:119], v186, v186 op_sel_hi:[0,0,0]
	s_nop 1
	v_mfma_scale_f32_16x16x128_f8f6f4 v[108:111], v[24:31], v[204:211], v[108:111], v186, v186 op_sel_hi:[0,0,0]
	s_setprio 0
	s_setprio 1
	s_nop 1
	v_mfma_scale_f32_16x16x128_f8f6f4 v[136:139], v[0:7], v[172:179], v[136:139], v186, v186 op_sel_hi:[0,0,0]
	s_nop 1
	v_mfma_scale_f32_16x16x128_f8f6f4 v[132:135], v[8:15], v[172:179], v[132:135], v186, v186 op_sel_hi:[0,0,0]
	s_nop 1
	v_mfma_scale_f32_16x16x128_f8f6f4 v[128:131], v[0:7], v[188:195], v[128:131], v186, v186 op_sel_hi:[0,0,0]
	s_nop 1
	v_mfma_scale_f32_16x16x128_f8f6f4 v[120:123], v[8:15], v[188:195], v[120:123], v186, v186 op_sel_hi:[0,0,0]
	s_nop 1
	v_mfma_scale_f32_16x16x128_f8f6f4 v[112:115], v[0:7], v[196:203], v[112:115], v186, v186 op_sel_hi:[0,0,0]
	s_nop 1
	v_mfma_scale_f32_16x16x128_f8f6f4 v[104:107], v[8:15], v[196:203], v[104:107], v186, v186 op_sel_hi:[0,0,0]
	s_nop 1
	v_mfma_scale_f32_16x16x128_f8f6f4 v[100:103], v[0:7], v[204:211], v[100:103], v186, v186 op_sel_hi:[0,0,0]
	s_nop 1
	v_mfma_scale_f32_16x16x128_f8f6f4 v[96:99], v[8:15], v[204:211], v[96:99], v186, v186 op_sel_hi:[0,0,0]
	s_setprio 0
	s_barrier
	s_add_i32 s61, s53, s42
	v_lshl_add_u64 v[172:173], s[38:39], 0, v[162:163]
	s_mov_b32 m0, s61
	ds_read_b128 v[188:191], v185 offset:16384
	ds_read_b128 v[192:195], v185 offset:17408
	ds_read_b128 v[196:199], v185 offset:18432
	ds_read_b128 v[200:203], v185 offset:19456
	ds_read_b128 v[204:207], v185 offset:20480
	ds_read_b128 v[208:211], v185 offset:21504
	ds_read_b128 v[212:215], v185 offset:22528
	ds_read_b128 v[216:219], v185 offset:23552
	global_load_lds_dwordx4 v[172:173], off
	s_add_i32 m0, s61, 0x2000
	s_add_u32 s62, s38, 0x200000
	v_lshl_add_u64 v[174:175], s[38:39], 0, v[160:161]
	s_addc_u32 s63, s39, 0
	s_add_i32 s61, s54, s42
	global_load_lds_dwordx4 v[174:175], off
	v_lshl_add_u64 v[176:177], s[62:63], 0, v[162:163]
	s_mov_b32 m0, s61
	v_lshl_add_u64 v[178:179], s[40:41], 0, v[160:161]
	global_load_lds_dwordx4 v[176:177], off
	v_lshl_add_u64 v[176:177], s[62:63], 0, v[160:161]
	s_add_i32 m0, s61, 0x2000
	s_nop 0
	global_load_lds_dwordx4 v[176:177], off
	v_lshl_add_u64 v[176:177], s[40:41], 0, v[162:163]
	s_mov_b32 m0, s31
	s_nop 0
	global_load_lds_dwordx4 v[176:177], off
	s_mov_b32 m0, s44
	s_nop 0
	global_load_lds_dwordx4 v[178:179], off
	s_waitcnt vmcnt(8)
	s_waitcnt lgkmcnt(0)
	s_barrier
	s_setprio 1
	s_waitcnt lgkmcnt(0)
	s_nop 1
	v_mfma_scale_f32_16x16x128_f8f6f4 v[92:95], v[16:23], v[188:195], v[92:95], v186, v186 op_sel_hi:[0,0,0]
	s_nop 1
	v_mfma_scale_f32_16x16x128_f8f6f4 v[88:91], v[24:31], v[188:195], v[88:91], v186, v186 op_sel_hi:[0,0,0]
	s_nop 1
	v_mfma_scale_f32_16x16x128_f8f6f4 v[84:87], v[16:23], v[196:203], v[84:87], v186, v186 op_sel_hi:[0,0,0]
	s_nop 1
	v_mfma_scale_f32_16x16x128_f8f6f4 v[80:83], v[24:31], v[196:203], v[80:83], v186, v186 op_sel_hi:[0,0,0]
	s_nop 1
	v_mfma_scale_f32_16x16x128_f8f6f4 v[76:79], v[16:23], v[204:211], v[76:79], v186, v186 op_sel_hi:[0,0,0]
	s_nop 1
	v_mfma_scale_f32_16x16x128_f8f6f4 v[64:67], v[24:31], v[204:211], v[64:67], v186, v186 op_sel_hi:[0,0,0]
	s_nop 1
	v_mfma_scale_f32_16x16x128_f8f6f4 v[52:55], v[16:23], v[212:219], v[52:55], v186, v186 op_sel_hi:[0,0,0]
	s_nop 1
	v_mfma_scale_f32_16x16x128_f8f6f4 v[44:47], v[24:31], v[212:219], v[44:47], v186, v186 op_sel_hi:[0,0,0]
	s_setprio 0
	s_setprio 1
	s_nop 1
	v_mfma_scale_f32_16x16x128_f8f6f4 v[72:75], v[0:7], v[188:195], v[72:75], v186, v186 op_sel_hi:[0,0,0]
	s_nop 1
	v_mfma_scale_f32_16x16x128_f8f6f4 v[68:71], v[8:15], v[188:195], v[68:71], v186, v186 op_sel_hi:[0,0,0]
	s_nop 1
	v_mfma_scale_f32_16x16x128_f8f6f4 v[60:63], v[0:7], v[196:203], v[60:63], v186, v186 op_sel_hi:[0,0,0]
	s_nop 1
	v_mfma_scale_f32_16x16x128_f8f6f4 v[56:59], v[8:15], v[196:203], v[56:59], v186, v186 op_sel_hi:[0,0,0]
	s_nop 1
	v_mfma_scale_f32_16x16x128_f8f6f4 v[48:51], v[0:7], v[204:211], v[48:51], v186, v186 op_sel_hi:[0,0,0]
	s_nop 1
	v_mfma_scale_f32_16x16x128_f8f6f4 v[40:43], v[8:15], v[204:211], v[40:43], v186, v186 op_sel_hi:[0,0,0]
	s_nop 1
	v_mfma_scale_f32_16x16x128_f8f6f4 v[36:39], v[0:7], v[212:219], v[36:39], v186, v186 op_sel_hi:[0,0,0]
	s_nop 1
	v_mfma_scale_f32_16x16x128_f8f6f4 v[32:35], v[8:15], v[212:219], v[32:35], v186, v186 op_sel_hi:[0,0,0]
	s_setprio 0
	s_barrier
	s_add_i32 s61, 0, 0x18000
	s_add_i32 s62, 0, 0x1c000
	v_add_u32_e32 v12, s61, v181
	v_add_u32_e32 v28, s62, v181
	ds_read_b128 v[0:3], v12
	ds_read_b128 v[4:7], v12 offset:1024
	ds_read_b128 v[8:11], v12 offset:2048
	ds_read_b128 v[12:15], v12 offset:3072
	ds_read_b128 v[16:19], v28
	ds_read_b128 v[20:23], v28 offset:1024
	ds_read_b128 v[24:27], v28 offset:2048
	ds_read_b128 v[28:31], v28 offset:3072
	s_add_u32 s40, s40, 0x200000
	s_addc_u32 s41, s41, 0
	s_mov_b32 m0, s45
	v_lshl_add_u64 v[220:221], s[40:41], 0, v[162:163]
	ds_read_b128 v[188:191], v185 offset:32768
	ds_read_b128 v[192:195], v185 offset:33792
	ds_read_b128 v[196:199], v185 offset:34816
	ds_read_b128 v[200:203], v185 offset:35840
	ds_read_b128 v[204:207], v185 offset:36864
	ds_read_b128 v[208:211], v185 offset:37888
	ds_read_b128 v[212:215], v185 offset:38912
	ds_read_b128 v[216:219], v185 offset:39936
	global_load_lds_dwordx4 v[220:221], off
	v_lshl_add_u64 v[220:221], s[40:41], 0, v[160:161]
	s_mov_b32 m0, s46
	s_nop 0
	global_load_lds_dwordx4 v[220:221], off
	s_waitcnt vmcnt(8)
	s_waitcnt lgkmcnt(0)
	s_barrier
	s_setprio 1
	s_waitcnt lgkmcnt(0)
	s_nop 1
	v_mfma_scale_f32_16x16x128_f8f6f4 v[156:159], v[0:7], v[188:195], v[156:159], v186, v186 op_sel_hi:[0,0,0]
	s_nop 1
	v_mfma_scale_f32_16x16x128_f8f6f4 v[152:155], v[8:15], v[188:195], v[152:155], v186, v186 op_sel_hi:[0,0,0]
	s_nop 1
	v_mfma_scale_f32_16x16x128_f8f6f4 v[148:151], v[0:7], v[196:203], v[148:151], v186, v186 op_sel_hi:[0,0,0]
	s_nop 1
	v_mfma_scale_f32_16x16x128_f8f6f4 v[144:147], v[8:15], v[196:203], v[144:147], v186, v186 op_sel_hi:[0,0,0]
	s_nop 1
	v_mfma_scale_f32_16x16x128_f8f6f4 v[140:143], v[0:7], v[204:211], v[140:143], v186, v186 op_sel_hi:[0,0,0]
	s_nop 1
	v_mfma_scale_f32_16x16x128_f8f6f4 v[124:127], v[8:15], v[204:211], v[124:127], v186, v186 op_sel_hi:[0,0,0]
	s_nop 1
	v_mfma_scale_f32_16x16x128_f8f6f4 v[116:119], v[0:7], v[212:219], v[116:119], v186, v186 op_sel_hi:[0,0,0]
	s_nop 1
	v_mfma_scale_f32_16x16x128_f8f6f4 v[108:111], v[8:15], v[212:219], v[108:111], v186, v186 op_sel_hi:[0,0,0]
	s_setprio 0
	s_setprio 1
	s_nop 1
	v_mfma_scale_f32_16x16x128_f8f6f4 v[136:139], v[16:23], v[188:195], v[136:139], v186, v186 op_sel_hi:[0,0,0]
	s_nop 1
	v_mfma_scale_f32_16x16x128_f8f6f4 v[132:135], v[24:31], v[188:195], v[132:135], v186, v186 op_sel_hi:[0,0,0]
	s_nop 1
	v_mfma_scale_f32_16x16x128_f8f6f4 v[128:131], v[16:23], v[196:203], v[128:131], v186, v186 op_sel_hi:[0,0,0]
	s_nop 1
	v_mfma_scale_f32_16x16x128_f8f6f4 v[120:123], v[24:31], v[196:203], v[120:123], v186, v186 op_sel_hi:[0,0,0]
	s_nop 1
	v_mfma_scale_f32_16x16x128_f8f6f4 v[112:115], v[16:23], v[204:211], v[112:115], v186, v186 op_sel_hi:[0,0,0]
	s_nop 1
	v_mfma_scale_f32_16x16x128_f8f6f4 v[104:107], v[24:31], v[204:211], v[104:107], v186, v186 op_sel_hi:[0,0,0]
	s_nop 1
	v_mfma_scale_f32_16x16x128_f8f6f4 v[100:103], v[16:23], v[212:219], v[100:103], v186, v186 op_sel_hi:[0,0,0]
	s_nop 1
	v_mfma_scale_f32_16x16x128_f8f6f4 v[96:99], v[24:31], v[212:219], v[96:99], v186, v186 op_sel_hi:[0,0,0]
	s_setprio 0
	s_barrier
	s_add_i32 s40, s61, s42
	v_lshl_add_u64 v[172:173], v[172:173], 0, s[6:7]
	s_mov_b32 m0, s40
	ds_read_b128 v[188:191], v185 offset:49152
	ds_read_b128 v[192:195], v185 offset:50176
	ds_read_b128 v[196:199], v185 offset:51200
	ds_read_b128 v[200:203], v185 offset:52224
	ds_read_b128 v[204:207], v185 offset:53248
	ds_read_b128 v[208:211], v185 offset:54272
	ds_read_b128 v[212:215], v185 offset:55296
	ds_read_b128 v[216:219], v185 offset:56320
	global_load_lds_dwordx4 v[172:173], off
	s_add_i32 m0, s40, 0x2000
	s_add_u32 s38, s38, 0x200080
	v_lshl_add_u64 v[172:173], v[174:175], 0, s[6:7]
	s_addc_u32 s39, s39, 0
	s_add_i32 s40, s62, s42
	global_load_lds_dwordx4 v[172:173], off
	v_lshl_add_u64 v[172:173], s[38:39], 0, v[162:163]
	s_mov_b32 m0, s40
	s_nop 0
	global_load_lds_dwordx4 v[172:173], off
	v_lshl_add_u64 v[172:173], s[38:39], 0, v[160:161]
	s_add_i32 m0, s40, 0x2000
	s_nop 0
	global_load_lds_dwordx4 v[172:173], off
	v_lshl_add_u64 v[172:173], v[176:177], 0, s[6:7]
	s_mov_b32 m0, s51
	s_nop 0
	global_load_lds_dwordx4 v[172:173], off
	v_lshl_add_u64 v[172:173], v[178:179], 0, s[6:7]
	s_mov_b32 m0, s52
	s_nop 0
	global_load_lds_dwordx4 v[172:173], off
	s_waitcnt vmcnt(8)
	s_waitcnt lgkmcnt(0)
	s_barrier
	s_setprio 1
	s_waitcnt lgkmcnt(0)
	s_nop 1
	v_mfma_scale_f32_16x16x128_f8f6f4 v[92:95], v[0:7], v[188:195], v[92:95], v186, v186 op_sel_hi:[0,0,0]
	s_nop 1
	v_mfma_scale_f32_16x16x128_f8f6f4 v[88:91], v[8:15], v[188:195], v[88:91], v186, v186 op_sel_hi:[0,0,0]
	s_nop 1
	v_mfma_scale_f32_16x16x128_f8f6f4 v[84:87], v[0:7], v[196:203], v[84:87], v186, v186 op_sel_hi:[0,0,0]
	s_nop 1
	v_mfma_scale_f32_16x16x128_f8f6f4 v[80:83], v[8:15], v[196:203], v[80:83], v186, v186 op_sel_hi:[0,0,0]
	s_nop 1
	v_mfma_scale_f32_16x16x128_f8f6f4 v[76:79], v[0:7], v[204:211], v[76:79], v186, v186 op_sel_hi:[0,0,0]
	s_nop 1
	v_mfma_scale_f32_16x16x128_f8f6f4 v[64:67], v[8:15], v[204:211], v[64:67], v186, v186 op_sel_hi:[0,0,0]
	s_nop 1
	v_mfma_scale_f32_16x16x128_f8f6f4 v[52:55], v[0:7], v[212:219], v[52:55], v186, v186 op_sel_hi:[0,0,0]
	s_nop 1
	v_mfma_scale_f32_16x16x128_f8f6f4 v[44:47], v[8:15], v[212:219], v[44:47], v186, v186 op_sel_hi:[0,0,0]
	s_setprio 0
	s_setprio 1
	s_nop 1
	v_mfma_scale_f32_16x16x128_f8f6f4 v[72:75], v[16:23], v[188:195], v[72:75], v186, v186 op_sel_hi:[0,0,0]
	s_nop 1
	v_mfma_scale_f32_16x16x128_f8f6f4 v[68:71], v[24:31], v[188:195], v[68:71], v186, v186 op_sel_hi:[0,0,0]
	s_nop 1
	v_mfma_scale_f32_16x16x128_f8f6f4 v[60:63], v[16:23], v[196:203], v[60:63], v186, v186 op_sel_hi:[0,0,0]
	s_nop 1
	v_mfma_scale_f32_16x16x128_f8f6f4 v[56:59], v[24:31], v[196:203], v[56:59], v186, v186 op_sel_hi:[0,0,0]
	s_nop 1
	v_mfma_scale_f32_16x16x128_f8f6f4 v[48:51], v[16:23], v[204:211], v[48:51], v186, v186 op_sel_hi:[0,0,0]
	s_nop 1
	v_mfma_scale_f32_16x16x128_f8f6f4 v[40:43], v[24:31], v[204:211], v[40:43], v186, v186 op_sel_hi:[0,0,0]
	s_nop 1
	v_mfma_scale_f32_16x16x128_f8f6f4 v[36:39], v[16:23], v[212:219], v[36:39], v186, v186 op_sel_hi:[0,0,0]
	s_nop 1
	v_mfma_scale_f32_16x16x128_f8f6f4 v[32:35], v[24:31], v[212:219], v[32:35], v186, v186 op_sel_hi:[0,0,0]
	s_add_i32 s60, s60, 2
	s_add_u32 s36, s36, 0x100
	s_addc_u32 s37, s37, 0
	s_add_u32 s58, s58, 0x100
	s_addc_u32 s59, s59, 0
	s_cmpk_lt_u32 s60, 0x7e
	s_setprio 0
	s_barrier
	s_cbranch_scc1 .LBB0_1019
	s_nop 15
	s_nop 15
	s_andn2_b64 vcc, exec, s[12:13]
	s_cbranch_vccnz .LBB0_1022
	s_barrier
